# attention: bias and K fragment LDS reads issued right after the tile barrier, overlapping the staging of the next tile
# baseline (speedup 1.0000x reference)
; #define LAS __attribute__((address_space(3)))
; template <bool BAND>
; __device__ __forceinline__ void tile_body(f32x16* o, float& l_reg, const bf16x8* qr, const LAS unsigned char* kbs, const LAS float* wb, int vb, float ci, int hi, int keybase, int qabs) {
;     ...
; #pragma unroll
;     for (int g4 = 0; g4 < 4; ++g4) {
;         const f32x4 ba = *(const LAS f32x4*)(wb + 8 * g4 + 4 * hi) + ci, bb = *(const LAS f32x4*)(wb + 32 + 8 * g4 + 4 * hi) + ci;
; #pragma unroll
;         for (int e = 0; e < 4; ++e) { p0[4 * g4 + e] = ba[e]; p1[4 * g4 + e] = bb[e]; }
;     }
; #pragma unroll
;     for (int d0 = 0; d0 < 4; ++d0) {
;         const bf16x8 b0 = *(const LAS bf16x8*)(kbs + d0 * 2048), b1 = *(const LAS bf16x8*)(kbs + d0 * 2048 + 512);
;         p0 = __builtin_amdgcn_mfma_f32_32x32x16_bf16(b0, qr[d0], p0, 0, 0, 0); p1 = __builtin_amdgcn_mfma_f32_32x32x16_bf16(b1, qr[d0], p1, 0, 0, 0); }
.LBB0_777:
	s_waitcnt lgkmcnt(0)
	s_barrier
	s_lshl_b32 s100, s70, 14
	v_add_u32_e32 v242, s100, v145
	s_lshl_b32 s100, s70, 8
	s_add_i32 s100, s53, s100
	v_lshl_add_u32 v243, v142, 2, s100
	ds_read_b128 v[34:37], v243 offset:32768
	ds_read_b128 v[38:41], v243 offset:32800
	ds_read_b128 v[42:45], v243 offset:32832
	ds_read_b128 v[46:49], v243 offset:32864
	ds_read_b128 v[50:53], v243 offset:32896
	ds_read_b128 v[54:57], v243 offset:32928
	ds_read_b128 v[58:61], v243 offset:32960
	ds_read_b128 v[62:65], v243 offset:32992
	ds_read_b128 v[154:157], v242
	ds_read_b128 v[158:161], v242 offset:512
	ds_read_b128 v[210:213], v242 offset:2048
	ds_read_b128 v[214:217], v242 offset:2560
	ds_read_b128 v[218:221], v242 offset:4096
	ds_read_b128 v[222:225], v242 offset:4608
	ds_read_b128 v[226:229], v242 offset:6144
	ds_read_b128 v[230:233], v242 offset:6656
	s_waitcnt vmcnt(6)
	s_nop 1
	v_add_f32_dpp v0, v140, v140 row_shl:1 row_mask:0xf bank_mask:0xf bound_ctrl:1
	s_nop 1
	v_add_f32_dpp v0, v0, v0 row_shl:2 row_mask:0xf bank_mask:0xf bound_ctrl:1
	s_nop 1
	v_add_f32_dpp v0, v0, v0 row_shl:4 row_mask:0xf bank_mask:0xf bound_ctrl:1
	s_nop 1
	v_add_f32_dpp v0, v0, v0 row_shl:8 row_mask:0xf bank_mask:0xf bound_ctrl:1
	s_nop 0
	v_readlane_b32 s28, v0, 16
	v_readlane_b32 s67, v0, 32
	v_readlane_b32 s66, v0, 48
	s_and_saveexec_b64 s[12:13], s[6:7]
	s_xor_b64 s[12:13], exec, s[12:13]
	s_cbranch_execz .LBB0_783
	s_and_saveexec_b64 s[64:65], s[8:9]
	s_xor_b64 s[64:65], exec, s[64:65]
	v_mov_b32_e32 v149, s66
	v_cndmask_b32_e64 v149, 0, v149, s[10:11]
	s_andn2_saveexec_b64 s[64:65], s[64:65]
	v_mov_b32_e32 v149, s66
	v_add_f32_e32 v149, s67, v149
	s_or_b64 exec, exec, s[64:65]
.LBB0_783:
	s_andn2_saveexec_b64 s[12:13], s[12:13]
	v_mov_b32_e32 v149, s67
	v_add_f32_e32 v149, s28, v149
	v_add_f32_e32 v149, s66, v149
	s_or_b64 exec, exec, s[12:13]
	v_add_f32_e32 v149, v0, v149
	s_xor_b32 s74, s70, 1
	v_add_f32_e32 v0, v150, v149
	s_lshl_b32 s12, s74, 8
	v_sub_f32_e32 v0, v0, v140
	s_add_i32 s71, s53, s12
	s_lshl_b32 s78, s74, 14
	s_max_i32 s12, s48, 4
	v_mul_f32_e32 v140, 0x3fb8aa3b, v0
	v_lshl_add_u32 v0, v137, 2, s71
	v_readfirstlane_b32 s76, v149
	v_add_u32_e32 v149, s78, v143
	s_add_i32 s28, s12, -4
	ds_write_b32 v0, v140 offset:32768
	ds_write_b128 v149, v[66:69]
	ds_write_b128 v149, v[74:77] offset:8192
	s_lshl_b64 s[12:13], s[28:29], 11
	s_waitcnt lgkmcnt(0)
	v_lshl_add_u64 v[66:67], v[110:111], 0, s[12:13]
	s_lshl_b64 s[12:13], s[28:29], 16
	global_load_dword v140, v[66:67], off
	v_lshl_add_u64 v[74:75], v[106:107], 0, s[12:13]
	global_load_dwordx4 v[66:69], v[74:75], off
	v_cndmask_b32_e64 v74, 0, 1, s[58:59]
	v_lshl_add_u64 v[152:153], v[108:109], 0, s[12:13]
	v_cmp_ne_u32_e64 s[12:13], 1, v74
	global_load_dwordx4 v[74:77], v[152:153], off
	s_andn2_b64 vcc, exec, s[58:59]
	s_cbranch_vccnz .LBB0_792
	s_and_b64 vcc, exec, s[98:99]
	s_cbranch_vccnz .LBB0_792
	s_sub_i32 s28, s75, 64
	s_cmp_gt_i32 s28, s73
	s_cbranch_scc1 .LBB0_792
	s_lshl_b32 s64, s70, 8
	s_lshl_b32 s28, s70, 14
	s_add_i32 s66, s53, s64
	s_cmp_lt_i32 s48, s72
	v_add_u32_e32 v151, s28, v144
	s_mov_b64 s[64:65], -1
	v_add_u32_e32 v152, s28, v145
	v_lshl_add_u32 v153, v142, 2, s66
	s_cbranch_scc1 .LBB0_789
	s_waitcnt lgkmcnt(4)
	v_pk_add_f32 v[56:57], v[118:119], v[56:57]
	s_waitcnt lgkmcnt(9)
	v_pk_add_f32 v[60:61], v[122:123], v[60:61]
	s_waitcnt lgkmcnt(8)
	v_pk_add_f32 v[64:65], v[126:127], v[64:65]
	v_pk_add_f32 v[52:53], v[114:115], v[52:53]
	v_pk_add_f32 v[62:63], v[124:125], v[62:63]
	v_pk_add_f32 v[58:59], v[120:121], v[58:59]
	v_pk_add_f32 v[54:55], v[116:117], v[54:55]
	v_pk_add_f32 v[50:51], v[112:113], v[50:51]
	v_pk_add_f32 v[48:49], v[126:127], v[48:49]
	v_pk_add_f32 v[44:45], v[122:123], v[44:45]
	v_pk_add_f32 v[40:41], v[118:119], v[40:41]
	v_pk_add_f32 v[36:37], v[114:115], v[36:37]
	v_pk_add_f32 v[46:47], v[124:125], v[46:47]
	v_pk_add_f32 v[42:43], v[120:121], v[42:43]
	v_pk_add_f32 v[38:39], v[116:117], v[38:39]
	v_pk_add_f32 v[34:35], v[112:113], v[34:35]
	s_waitcnt lgkmcnt(6)
	v_mfma_f32_32x32x16_bf16 v[50:65], v[158:161], v[94:97], v[50:65]
	v_mfma_f32_32x32x16_bf16 v[34:49], v[154:157], v[94:97], v[34:49]
	s_waitcnt lgkmcnt(4)
	v_mfma_f32_32x32x16_bf16 v[50:65], v[214:217], v[98:101], v[50:65]
	v_mfma_f32_32x32x16_bf16 v[34:49], v[210:213], v[98:101], v[34:49]
	s_waitcnt lgkmcnt(2)
	v_mfma_f32_32x32x16_bf16 v[50:65], v[222:225], v[102:105], v[50:65]
	v_mfma_f32_32x32x16_bf16 v[34:49], v[218:221], v[102:105], v[34:49]
	s_waitcnt lgkmcnt(1)
	v_mfma_f32_32x32x16_bf16 v[50:65], v[230:233], v[90:93], v[50:65]
	v_add_u32_e32 v154, s75, v142
	v_subrev_u32_e32 v156, 32, v154
	v_subrev_u32_e32 v155, 64, v154
	v_cmp_le_i32_e32 vcc, v156, v147
	s_waitcnt lgkmcnt(0)
; __device__ __forceinline__ void pv(f32x16* o, int vb, bf16x8 pa0, bf16x8 pa1, bf16x8 pa2, bf16x8 pa3) {
; #pragma unroll
;     for (int d0 = 0; d0 < 2; ++d0) { s16x4 lo[4], hi[4];
; #pragma unroll
;         for (int ks = 0; ks < 4; ++ks) {
;             asm volatile("ds_read_b64_tr_b16 %0,%1 offset:%c2" : "=&v"(lo[ks]) : "v"(vb), "i"(d0 * 4096 + ks * 1024) : "memory");
;             asm volatile("ds_read_b64_tr_b16 %0,%1 offset:%c2" : "=&v"(hi[ks]) : "v"(vb), "i"(d0 * 4096 + ks * 1024 + 512) : "memory"); }
;         asm volatile("s_waitcnt lgkmcnt(0)" ::: "memory"); __builtin_amdgcn_sched_barrier(0);
;     ...
;         o[d0] = __builtin_amdgcn_mfma_f32_32x32x16_bf16(pa0, PK(0), o[d0], 0, 0, 0);
;         o[d0] = __builtin_amdgcn_mfma_f32_32x32x16_bf16(pa1, PK(1), o[d0], 0, 0, 0);
;         o[d0] = __builtin_amdgcn_mfma_f32_32x32x16_bf16(pa2, PK(2), o[d0], 0, 0, 0);
;         o[d0] = __builtin_amdgcn_mfma_f32_32x32x16_bf16(pa3, PK(3), o[d0], 0, 0, 0);
;     ...
;     }
; template <bool BAND>
; __device__ __forceinline__ void tile_body(f32x16* o, float& l_reg, const bf16x8* qr, const LAS unsigned char* kbs, const LAS float* wb, int vb, float ci, int hi, int keybase, int qabs) {
;     ...
;     if (BAND) {
; #pragma unroll
;         for (int r = 0; r < 16; ++r) { const int key = keybase + 8 * (r >> 2) + (r & 3); if (key > qabs) p0[r] = -INFINITY; if (key + 32 > qabs) p1[r] = -INFINITY; }
;     }
;     f32x2 s2 = {0.f, 0.f};
; #pragma unroll
;     for (int r = 0; r < 16; r += 2) {
;         p0[r] = __builtin_amdgcn_exp2f(p0[r]); p0[r + 1] = __builtin_amdgcn_exp2f(p0[r + 1]); p1[r] = __builtin_amdgcn_exp2f(p1[r]); p1[r + 1] = __builtin_amdgcn_exp2f(p1[r + 1]);
;         s2 += (f32x2){p0[r], p0[r + 1]}; s2 += (f32x2){p1[r], p1[r + 1]}; }
;     l_reg += s2.x + s2.y;
;     u32x4 pw0, pw1, pw2, pw3;
;     pw0 = (u32x4){cvtpk(p0[0], p0[1]), cvtpk(p0[2], p0[3]), cvtpk(p0[4], p0[5]), cvtpk(p0[6], p0[7])};
;     pw1 = (u32x4){cvtpk(p0[8], p0[9]), cvtpk(p0[10], p0[11]), cvtpk(p0[12], p0[13]), cvtpk(p0[14], p0[15])};
;     pw2 = (u32x4){cvtpk(p1[0], p1[1]), cvtpk(p1[2], p1[3]), cvtpk(p1[4], p1[5]), cvtpk(p1[6], p1[7])};
;     pw3 = (u32x4){cvtpk(p1[8], p1[9]), cvtpk(p1[10], p1[11]), cvtpk(p1[12], p1[13]), cvtpk(p1[14], p1[15])};
;     pv(o, vb, __builtin_bit_cast(bf16x8, pw0), __builtin_bit_cast(bf16x8, pw1), __builtin_bit_cast(bf16x8, pw2), __builtin_bit_cast(bf16x8, pw3));
	v_mfma_f32_32x32x16_bf16 v[34:49], v[226:229], v[90:93], v[34:49]
	s_nop 5
	v_cndmask_b32_e32 v50, v134, v50, vcc
	v_cmp_lt_i32_e32 vcc, v155, v147
	s_nop 3
	v_cndmask_b32_e32 v35, v134, v35, vcc
	v_cmp_le_i32_e32 vcc, v155, v147
	v_subrev_u32_e32 v155, 31, v154
	v_exp_f32_e32 v35, v35
	v_cndmask_b32_e32 v34, v134, v34, vcc
	v_cmp_le_i32_e32 vcc, v155, v147
	v_subrev_u32_e32 v155, 62, v154
	v_exp_f32_e32 v34, v34
	v_cndmask_b32_e32 v51, v134, v51, vcc
	v_cmp_le_i32_e32 vcc, v155, v147
	s_nop 1
	v_cndmask_b32_e32 v155, v134, v36, vcc
	v_subrev_u32_e32 v36, 30, v154
	v_cmp_le_i32_e32 vcc, v36, v147
	v_subrev_u32_e32 v36, 61, v154
	s_nop 0
	v_cndmask_b32_e32 v52, v134, v52, vcc
	v_cmp_le_i32_e32 vcc, v36, v147
	v_subrev_u32_e32 v36, 29, v154
	s_nop 0
	v_cndmask_b32_e32 v156, v134, v37, vcc
	v_cmp_le_i32_e32 vcc, v36, v147
	v_subrev_u32_e32 v36, 56, v154
	v_exp_f32_e32 v37, v51
	v_cndmask_b32_e32 v53, v134, v53, vcc
	v_cmp_le_i32_e32 vcc, v36, v147
	v_subrev_u32_e32 v36, 24, v154
	s_nop 0
	v_cndmask_b32_e32 v157, v134, v38, vcc
	v_cmp_le_i32_e32 vcc, v36, v147
	v_subrev_u32_e32 v36, 55, v154
	v_exp_f32_e32 v38, v155
	v_cndmask_b32_e32 v54, v134, v54, vcc
	v_cmp_le_i32_e32 vcc, v36, v147
	v_subrev_u32_e32 v36, 23, v154
	s_nop 0
	v_cndmask_b32_e32 v158, v134, v39, vcc
	v_cmp_le_i32_e32 vcc, v36, v147
	v_subrev_u32_e32 v36, 54, v154
	v_exp_f32_e32 v39, v156
	v_cndmask_b32_e32 v55, v134, v55, vcc
	v_cmp_le_i32_e32 vcc, v36, v147
	v_subrev_u32_e32 v36, 22, v154
	v_cvt_pk_bf16_f32 v156, v34, v35
	v_cndmask_b32_e32 v159, v134, v40, vcc
	v_cmp_le_i32_e32 vcc, v36, v147
	v_subrev_u32_e32 v36, 53, v154
	v_exp_f32_e32 v40, v52
	v_cndmask_b32_e32 v56, v134, v56, vcc
	v_cmp_le_i32_e32 vcc, v36, v147
	v_subrev_u32_e32 v36, 21, v154
	s_nop 0
	v_cndmask_b32_e32 v160, v134, v41, vcc
	v_cmp_le_i32_e32 vcc, v36, v147
	v_subrev_u32_e32 v36, 48, v154
	v_exp_f32_e32 v41, v53
	v_cndmask_b32_e32 v57, v134, v57, vcc
	v_cmp_le_i32_e32 vcc, v36, v147
	v_add_u32_e32 v36, -16, v154
	v_exp_f32_e32 v51, v57
	v_cndmask_b32_e32 v161, v134, v42, vcc
	v_cmp_le_i32_e32 vcc, v36, v147
	v_subrev_u32_e32 v36, 47, v154
	v_exp_f32_e32 v52, v161
	v_cndmask_b32_e32 v58, v134, v58, vcc
	v_cmp_le_i32_e32 vcc, v36, v147
	v_add_u32_e32 v36, -15, v154
	s_nop 0
	v_cndmask_b32_e32 v162, v134, v43, vcc
	v_cmp_le_i32_e32 vcc, v36, v147
	v_subrev_u32_e32 v36, 46, v154
	v_pk_add_f32 v[42:43], v[34:35], 0 op_sel_hi:[1,0]
	v_cndmask_b32_e32 v59, v134, v59, vcc
	v_cmp_le_i32_e32 vcc, v36, v147
	v_add_u32_e32 v36, -14, v154
	v_exp_f32_e32 v53, v162
	v_cndmask_b32_e32 v163, v134, v44, vcc
	v_cmp_le_i32_e32 vcc, v36, v147
	v_subrev_u32_e32 v36, 45, v154
	v_exp_f32_e32 v44, v157
	v_cndmask_b32_e32 v60, v134, v60, vcc
	v_cmp_le_i32_e32 vcc, v36, v147
	v_add_u32_e32 v36, -13, v154
	v_cvt_pk_bf16_f32 v157, v38, v39
	v_cndmask_b32_e32 v164, v134, v45, vcc
	v_cmp_le_i32_e32 vcc, v36, v147
	v_subrev_u32_e32 v36, 40, v154
	v_exp_f32_e32 v45, v158
	v_cndmask_b32_e32 v61, v134, v61, vcc
	v_cmp_le_i32_e32 vcc, v36, v147
	v_add_u32_e32 v36, -8, v154
	v_exp_f32_e32 v57, v164
	v_cndmask_b32_e32 v165, v134, v46, vcc
	v_cmp_le_i32_e32 vcc, v36, v147
	v_subrev_u32_e32 v36, 39, v154
	v_exp_f32_e32 v46, v54
	v_cndmask_b32_e32 v62, v134, v62, vcc
	v_cmp_le_i32_e32 vcc, v36, v147
	v_add_u32_e32 v36, -7, v154
	v_exp_f32_e32 v54, v58
	v_cndmask_b32_e32 v166, v134, v47, vcc
	v_cmp_le_i32_e32 vcc, v36, v147
	v_subrev_u32_e32 v36, 38, v154
	v_exp_f32_e32 v47, v55
	v_cndmask_b32_e32 v63, v134, v63, vcc
	v_cmp_le_i32_e32 vcc, v36, v147
	v_add_u32_e32 v36, -6, v154
	v_exp_f32_e32 v55, v59
	v_cndmask_b32_e32 v167, v134, v48, vcc
	v_cmp_le_i32_e32 vcc, v36, v147
	v_subrev_u32_e32 v36, 37, v154
	v_exp_f32_e32 v48, v159
	v_cndmask_b32_e32 v168, v134, v64, vcc
	v_cmp_le_i32_e32 vcc, v36, v147
	v_add_u32_e32 v36, -5, v154
	v_exp_f32_e32 v58, v60
	v_cndmask_b32_e32 v169, v134, v49, vcc
	v_cmp_le_i32_e32 vcc, v36, v147
	v_exp_f32_e32 v36, v50
	v_exp_f32_e32 v49, v160
	v_exp_f32_e32 v50, v56
	v_exp_f32_e32 v56, v163
	v_pk_add_f32 v[42:43], v[36:37], v[42:43]
	v_exp_f32_e32 v59, v61
	v_pk_add_f32 v[42:43], v[38:39], v[42:43]
	v_exp_f32_e32 v64, v167
	v_pk_add_f32 v[42:43], v[40:41], v[42:43]
	v_cvt_pk_bf16_f32 v167, v50, v51
	v_pk_add_f32 v[42:43], v[44:45], v[42:43]
	v_exp_f32_e32 v60, v165
	v_pk_add_f32 v[42:43], v[46:47], v[42:43]
	v_exp_f32_e32 v61, v166
	v_pk_add_f32 v[42:43], v[48:49], v[42:43]
	v_cvt_pk_bf16_f32 v160, v52, v53
	v_pk_add_f32 v[42:43], v[50:51], v[42:43]
	ds_read_b64_tr_b16 v[50:51],v151 offset:0
	v_exp_f32_e32 v62, v62
	v_pk_add_f32 v[42:43], v[52:53], v[42:43]
	ds_read_b64_tr_b16 v[52:53],v151 offset:512
	v_exp_f32_e32 v63, v63
	v_pk_add_f32 v[42:43], v[54:55], v[42:43]
	v_exp_f32_e32 v172, v168
	v_cvt_pk_bf16_f32 v168, v54, v55
	ds_read_b64_tr_b16 v[54:55],v151 offset:1024
	v_cndmask_b32_e32 v154, v134, v65, vcc
	v_pk_add_f32 v[42:43], v[56:57], v[42:43]
	v_exp_f32_e32 v65, v169
	v_cvt_pk_bf16_f32 v161, v56, v57
	ds_read_b64_tr_b16 v[56:57],v151 offset:1536
	v_pk_add_f32 v[42:43], v[58:59], v[42:43]
	v_exp_f32_e32 v173, v154
	v_cvt_pk_bf16_f32 v169, v58, v59
	ds_read_b64_tr_b16 v[58:59],v151 offset:2048
	v_pk_add_f32 v[42:43], v[60:61], v[42:43]
	v_cvt_pk_bf16_f32 v162, v60, v61
	ds_read_b64_tr_b16 v[60:61],v151 offset:2560
	v_pk_add_f32 v[42:43], v[62:63], v[42:43]
	v_cvt_pk_bf16_f32 v170, v62, v63
	ds_read_b64_tr_b16 v[62:63],v151 offset:3072
	v_pk_add_f32 v[42:43], v[64:65], v[42:43]
	v_cvt_pk_bf16_f32 v163, v64, v65
	ds_read_b64_tr_b16 v[64:65],v151 offset:3584
	v_pk_add_f32 v[42:43], v[172:173], v[42:43]
	s_waitcnt lgkmcnt(0)
	v_cvt_pk_bf16_f32 v158, v44, v45
	v_add_f32_e32 v42, v42, v43
	v_add_f32_e32 v154, v148, v42
	v_cvt_pk_bf16_f32 v159, v48, v49
	v_cvt_pk_bf16_f32 v164, v36, v37
	v_cvt_pk_bf16_f32 v165, v40, v41
	v_cvt_pk_bf16_f32 v166, v46, v47
	v_cvt_pk_bf16_f32 v171, v172, v173
	v_mfma_f32_32x32x16_bf16 v[2:17], v[156:159], v[50:53], v[2:17]
	ds_read_b64_tr_b16 v[172:173],v151 offset:4096
	ds_read_b64_tr_b16 v[174:175],v151 offset:4608
	ds_read_b64_tr_b16 v[176:177],v151 offset:5120
	ds_read_b64_tr_b16 v[178:179],v151 offset:5632
	ds_read_b64_tr_b16 v[180:181],v151 offset:6144
	ds_read_b64_tr_b16 v[182:183],v151 offset:6656
	ds_read_b64_tr_b16 v[184:185],v151 offset:7168
	v_mfma_f32_32x32x16_bf16 v[2:17], v[160:163], v[54:57], v[2:17]
	ds_read_b64_tr_b16 v[186:187],v151 offset:7680
	s_waitcnt lgkmcnt(0)
	v_mfma_f32_32x32x16_bf16 v[2:17], v[164:167], v[58:61], v[2:17]
	v_mfma_f32_32x32x16_bf16 v[2:17], v[168:171], v[62:65], v[2:17]
	v_mfma_f32_32x32x16_bf16 v[18:33], v[156:159], v[172:175], v[18:33]
	s_mov_b64 s[64:65], 0
	v_mfma_f32_32x32x16_bf16 v[18:33], v[160:163], v[176:179], v[18:33]
	v_mfma_f32_32x32x16_bf16 v[18:33], v[164:167], v[180:183], v[18:33]
	v_mfma_f32_32x32x16_bf16 v[18:33], v[168:171], v[184:187], v[18:33]
; #define LAS __attribute__((address_space(3)))
; __device__ __forceinline__ unsigned cvtpk(float lo, float hi) { typedef __bf16 bf16x2_t __attribute__((ext_vector_type(2))); f32x2 v = {lo, hi}; bf16x2_t b = __builtin_convertvector(v, bf16x2_t); return __builtin_bit_cast(unsigned, b); }
; template <bool BAND>
; __device__ __forceinline__ void tile_body(f32x16* o, float& l_reg, const bf16x8* qr, const LAS unsigned char* kbs, const LAS float* wb, int vb, float ci, int hi, int keybase, int qabs) {
;     ...
; #pragma unroll
;     for (int g4 = 0; g4 < 4; ++g4) {
;         const f32x4 ba = *(const LAS f32x4*)(wb + 8 * g4 + 4 * hi) + ci, bb = *(const LAS f32x4*)(wb + 32 + 8 * g4 + 4 * hi) + ci;
; #pragma unroll
;         for (int e = 0; e < 4; ++e) { p0[4 * g4 + e] = ba[e]; p1[4 * g4 + e] = bb[e]; }
;     }
; #pragma unroll
;     for (int d0 = 0; d0 < 4; ++d0) {
;         const bf16x8 b0 = *(const LAS bf16x8*)(kbs + d0 * 2048), b1 = *(const LAS bf16x8*)(kbs + d0 * 2048 + 512);
;         p0 = __builtin_amdgcn_mfma_f32_32x32x16_bf16(b0, qr[d0], p0, 0, 0, 0); p1 = __builtin_amdgcn_mfma_f32_32x32x16_bf16(b1, qr[d0], p1, 0, 0, 0); }
;     if (BAND) {
; #pragma unroll
;         for (int r = 0; r < 16; ++r) { const int key = keybase + 8 * (r >> 2) + (r & 3); if (key > qabs) p0[r] = -INFINITY; if (key + 32 > qabs) p1[r] = -INFINITY; }
;     }
;     f32x2 s2 = {0.f, 0.f};
; #pragma unroll
;     for (int r = 0; r < 16; r += 2) {
;         p0[r] = __builtin_amdgcn_exp2f(p0[r]); p0[r + 1] = __builtin_amdgcn_exp2f(p0[r + 1]); p1[r] = __builtin_amdgcn_exp2f(p1[r]); p1[r + 1] = __builtin_amdgcn_exp2f(p1[r + 1]);
;         s2 += (f32x2){p0[r], p0[r + 1]}; s2 += (f32x2){p1[r], p1[r + 1]}; }
;     l_reg += s2.x + s2.y;
;     u32x4 pw0, pw1, pw2, pw3;
;     pw0 = (u32x4){cvtpk(p0[0], p0[1]), cvtpk(p0[2], p0[3]), cvtpk(p0[4], p0[5]), cvtpk(p0[6], p0[7])};
;     pw1 = (u32x4){cvtpk(p0[8], p0[9]), cvtpk(p0[10], p0[11]), cvtpk(p0[12], p0[13]), cvtpk(p0[14], p0[15])};
;     pw2 = (u32x4){cvtpk(p1[0], p1[1]), cvtpk(p1[2], p1[3]), cvtpk(p1[4], p1[5]), cvtpk(p1[6], p1[7])};
;     pw3 = (u32x4){cvtpk(p1[8], p1[9]), cvtpk(p1[10], p1[11]), cvtpk(p1[12], p1[13]), cvtpk(p1[14], p1[15])};
;     pv(o, vb, __builtin_bit_cast(bf16x8, pw0), __builtin_bit_cast(bf16x8, pw1), __builtin_bit_cast(bf16x8, pw2), __builtin_bit_cast(bf16x8, pw3));
.LBB0_789:
	s_andn2_b64 vcc, exec, s[64:65]
	s_cbranch_vccnz .Lmy_attjoin_A
	s_nop 4
	s_nop 0
	s_waitcnt lgkmcnt(6)
	v_pk_add_f32 v[48:49], v[126:127], v[48:49]
	v_pk_add_f32 v[44:45], v[122:123], v[44:45]
	v_pk_add_f32 v[40:41], v[118:119], v[40:41]
	v_pk_add_f32 v[36:37], v[114:115], v[36:37]
	v_pk_add_f32 v[46:47], v[124:125], v[46:47]
	v_pk_add_f32 v[42:43], v[120:121], v[42:43]
	v_pk_add_f32 v[38:39], v[116:117], v[38:39]
	v_pk_add_f32 v[34:35], v[112:113], v[34:35]
	s_waitcnt lgkmcnt(8)
	v_pk_add_f32 v[64:65], v[126:127], v[64:65]
	v_pk_add_f32 v[60:61], v[122:123], v[60:61]
	s_waitcnt lgkmcnt(7)
	v_mfma_f32_32x32x16_bf16 v[34:49], v[154:157], v[94:97], v[34:49]
	v_add_f32_e64 v56, v118, v56
	v_add_f32_e64 v57, v119, v57
	v_add_f32_e64 v52, v114, v52
	v_add_f32_e64 v53, v115, v53
	v_add_f32_e64 v62, v124, v62
	v_add_f32_e64 v63, v125, v63
	v_pk_add_f32 v[58:59], v[120:121], v[58:59]
	v_pk_add_f32 v[54:55], v[116:117], v[54:55]
	v_pk_add_f32 v[50:51], v[112:113], v[50:51]
	s_waitcnt lgkmcnt(6)
	s_nop 0
	v_mfma_f32_32x32x16_bf16 v[50:65], v[158:161], v[94:97], v[50:65]
	s_waitcnt lgkmcnt(5)
	v_mfma_f32_32x32x16_bf16 v[34:49], v[210:213], v[98:101], v[34:49]
	s_waitcnt lgkmcnt(4)
	v_mfma_f32_32x32x16_bf16 v[50:65], v[214:217], v[98:101], v[50:65]
	s_waitcnt lgkmcnt(3)
	v_mfma_f32_32x32x16_bf16 v[34:49], v[218:221], v[102:105], v[34:49]
	s_waitcnt lgkmcnt(2)
	v_mfma_f32_32x32x16_bf16 v[50:65], v[222:225], v[102:105], v[50:65]
	s_waitcnt lgkmcnt(1)
	v_mfma_f32_32x32x16_bf16 v[34:49], v[226:229], v[90:93], v[34:49]
	s_waitcnt lgkmcnt(0)
	v_mfma_f32_32x32x16_bf16 v[50:65], v[230:233], v[90:93], v[50:65]
	s_nop 9
	v_exp_f32_e32 v34, v34
	v_exp_f32_e32 v35, v35
	v_exp_f32_e32 v36, v36
	v_exp_f32_e32 v37, v37
	v_exp_f32_e32 v38, v38
	v_pk_add_f32 v[152:153], v[34:35], 0 op_sel_hi:[1,0]
	v_exp_f32_e32 v39, v39
	v_exp_f32_e32 v50, v50
	v_exp_f32_e32 v51, v51
	v_exp_f32_e32 v52, v52
	v_exp_f32_e32 v53, v53
	v_exp_f32_e32 v54, v54
	v_pk_add_f32 v[152:153], v[50:51], v[152:153]
	v_exp_f32_e32 v55, v55
	v_pk_add_f32 v[152:153], v[36:37], v[152:153]
	v_exp_f32_e32 v40, v40
	v_exp_f32_e32 v41, v41
	v_pk_add_f32 v[152:153], v[52:53], v[152:153]
	v_exp_f32_e32 v56, v56
	v_exp_f32_e32 v57, v57
	v_pk_add_f32 v[152:153], v[38:39], v[152:153]
	v_exp_f32_e32 v42, v42
	v_exp_f32_e32 v43, v43
	v_pk_add_f32 v[152:153], v[54:55], v[152:153]
	v_exp_f32_e32 v58, v58
	v_exp_f32_e32 v59, v59
	v_pk_add_f32 v[152:153], v[40:41], v[152:153]
	v_exp_f32_e32 v44, v44
	v_exp_f32_e32 v45, v45
	v_pk_add_f32 v[152:153], v[56:57], v[152:153]
	v_exp_f32_e32 v60, v60
	v_exp_f32_e32 v61, v61
	v_pk_add_f32 v[152:153], v[42:43], v[152:153]
	v_exp_f32_e32 v46, v46
	v_exp_f32_e32 v47, v47
	v_cvt_pk_bf16_f32 v34, v34, v35
	v_cvt_pk_bf16_f32 v35, v36, v37
	v_cvt_pk_bf16_f32 v36, v38, v39
	v_cvt_pk_bf16_f32 v38, v42, v43
	v_cvt_pk_bf16_f32 v42, v50, v51
	ds_read_b64_tr_b16 v[50:51],v151 offset:0
	v_pk_add_f32 v[152:153], v[58:59], v[152:153]
	v_exp_f32_e32 v62, v62
	v_exp_f32_e32 v63, v63
	v_cvt_pk_bf16_f32 v43, v52, v53
	ds_read_b64_tr_b16 v[52:53],v151 offset:512
	v_pk_add_f32 v[152:153], v[44:45], v[152:153]
	v_exp_f32_e32 v48, v48
	v_exp_f32_e32 v49, v49
	v_cvt_pk_bf16_f32 v39, v44, v45
	v_cvt_pk_bf16_f32 v44, v54, v55
	ds_read_b64_tr_b16 v[54:55],v151 offset:1024
	v_pk_add_f32 v[152:153], v[60:61], v[152:153]
	v_exp_f32_e32 v64, v64
	v_exp_f32_e32 v65, v65
	v_cvt_pk_bf16_f32 v45, v56, v57
	ds_read_b64_tr_b16 v[56:57],v151 offset:1536
	v_pk_add_f32 v[152:153], v[46:47], v[152:153]
	v_cvt_pk_bf16_f32 v37, v40, v41
	v_cvt_pk_bf16_f32 v40, v46, v47
	v_cvt_pk_bf16_f32 v46, v58, v59
	ds_read_b64_tr_b16 v[58:59],v151 offset:2048
	v_pk_add_f32 v[152:153], v[62:63], v[152:153]
	v_cvt_pk_bf16_f32 v47, v60, v61
	ds_read_b64_tr_b16 v[60:61],v151 offset:2560
	v_pk_add_f32 v[152:153], v[48:49], v[152:153]
	v_cvt_pk_bf16_f32 v41, v48, v49
	v_cvt_pk_bf16_f32 v48, v62, v63
	ds_read_b64_tr_b16 v[62:63],v151 offset:3072
	v_pk_add_f32 v[152:153], v[64:65], v[152:153]
	v_cvt_pk_bf16_f32 v49, v64, v65
	ds_read_b64_tr_b16 v[64:65],v151 offset:3584
	s_waitcnt lgkmcnt(0)
	v_add_f32_e32 v152, v152, v153
	v_add_f32_e32 v154, v148, v152
	v_mfma_f32_32x32x16_bf16 v[2:17], v[34:37], v[50:53], v[2:17]
	ds_read_b64_tr_b16 v[50:51],v151 offset:4096
	ds_read_b64_tr_b16 v[52:53],v151 offset:4608
	v_mfma_f32_32x32x16_bf16 v[2:17], v[38:41], v[54:57], v[2:17]
	ds_read_b64_tr_b16 v[54:55],v151 offset:5120
	ds_read_b64_tr_b16 v[56:57],v151 offset:5632
	v_mfma_f32_32x32x16_bf16 v[2:17], v[42:45], v[58:61], v[2:17]
	ds_read_b64_tr_b16 v[58:59],v151 offset:6144
	ds_read_b64_tr_b16 v[60:61],v151 offset:6656
	ds_read_b64_tr_b16 v[156:157],v151 offset:7168
	ds_read_b64_tr_b16 v[158:159],v151 offset:7680
	s_waitcnt lgkmcnt(0)
	v_mfma_f32_32x32x16_bf16 v[2:17], v[46:49], v[62:65], v[2:17]
	v_mfma_f32_32x32x16_bf16 v[18:33], v[34:37], v[50:53], v[18:33]
	v_mfma_f32_32x32x16_bf16 v[18:33], v[38:41], v[54:57], v[18:33]
	v_mfma_f32_32x32x16_bf16 v[18:33], v[42:45], v[58:61], v[18:33]
	v_mfma_f32_32x32x16_bf16 v[18:33], v[46:49], v[156:159], v[18:33]

.LBB0_792:
	s_cmp_lg_u32 s48, 0
	v_fma_f32 v151, v150, s50, -v146
	s_cselect_b64 s[64:65], -1, 0
	v_cmp_nlt_f32_e64 s[66:67], v151, -v131
	v_fma_f32 v196, v150, s50, -v197
	v_cmp_lt_f32_e64 s[100:101], v196, -v131
	s_nop 3
	s_or_b64 s[98:99], s[98:99], s[100:101]
	s_and_b64 s[68:69], s[64:65], s[66:67]
	s_mov_b64 s[66:67], -1
	s_and_saveexec_b64 s[64:65], s[68:69]
	s_cbranch_execz .LBB0_776
	s_waitcnt lgkmcnt(0)
	s_barrier
	v_add_u32_e32 v242, s78, v145
	v_lshl_add_u32 v243, v142, 2, s71
	ds_read_b128 v[34:37], v243 offset:32768
	ds_read_b128 v[38:41], v243 offset:32800
	ds_read_b128 v[42:45], v243 offset:32832
	ds_read_b128 v[46:49], v243 offset:32864
	ds_read_b128 v[50:53], v243 offset:32896
	ds_read_b128 v[54:57], v243 offset:32928
	ds_read_b128 v[58:61], v243 offset:32960
	ds_read_b128 v[62:65], v243 offset:32992
	ds_read_b128 v[154:157], v242
	ds_read_b128 v[158:161], v242 offset:512
	ds_read_b128 v[210:213], v242 offset:2048
	ds_read_b128 v[214:217], v242 offset:2560
	ds_read_b128 v[218:221], v242 offset:4096
	ds_read_b128 v[222:225], v242 offset:4608
	ds_read_b128 v[226:229], v242 offset:6144
	ds_read_b128 v[230:233], v242 offset:6656
	s_waitcnt vmcnt(6)
	s_nop 1
	v_add_f32_dpp v151, v141, v141 row_shl:1 row_mask:0xf bank_mask:0xf bound_ctrl:1
	s_nop 1
	v_add_f32_dpp v151, v151, v151 row_shl:2 row_mask:0xf bank_mask:0xf bound_ctrl:1
	s_nop 1
	v_add_f32_dpp v151, v151, v151 row_shl:4 row_mask:0xf bank_mask:0xf bound_ctrl:1
	s_nop 1
	v_add_f32_dpp v152, v151, v151 row_shl:8 row_mask:0xf bank_mask:0xf bound_ctrl:1
	s_nop 0
	v_readlane_b32 s28, v152, 16
	v_readlane_b32 s79, v152, 32
	v_readlane_b32 s77, v152, 48
	s_and_saveexec_b64 s[66:67], s[6:7]
	s_xor_b64 s[66:67], exec, s[66:67]
	s_cbranch_execz .LBB0_799
	s_and_saveexec_b64 s[68:69], s[8:9]
	s_xor_b64 s[68:69], exec, s[68:69]
	v_mov_b32_e32 v151, s77
	v_cndmask_b32_e64 v153, 0, v151, s[10:11]
	s_andn2_saveexec_b64 s[68:69], s[68:69]
	v_mov_b32_e32 v151, s77
	v_add_f32_e32 v153, s79, v151
	s_or_b64 exec, exec, s[68:69]
.LBB0_799:
	s_andn2_saveexec_b64 s[66:67], s[66:67]
	v_mov_b32_e32 v151, s79
	v_add_f32_e32 v151, s28, v151
	v_add_f32_e32 v153, s77, v151
	s_or_b64 exec, exec, s[66:67]
	v_add_f32_e32 v151, s76, v150
	v_add_f32_e32 v150, v152, v153
	v_add_f32_e32 v152, v151, v150
	s_lshl_b32 s28, s70, 8
	v_sub_f32_e32 v141, v152, v141
	s_add_i32 s76, s53, s28
	v_mul_f32_e32 v141, 0x3fb8aa3b, v141
	v_lshl_add_u32 v152, v137, 2, s76
	s_lshl_b32 s77, s70, 14
	ds_write_b32 v152, v141 offset:32768
	v_add_u32_e32 v141, s77, v143
	s_max_i32 s28, s48, 5
	ds_write_b128 v141, v[70:73]
	ds_write_b128 v141, v[82:85] offset:8192
	s_add_i32 s28, s28, -5
	s_waitcnt lgkmcnt(0)
	s_lshl_b64 s[66:67], s[28:29], 11
	v_lshl_add_u64 v[70:71], v[110:111], 0, s[66:67]
	global_load_dword v141, v[70:71], off
	s_lshl_b64 s[66:67], s[28:29], 16
	v_lshl_add_u64 v[82:83], v[106:107], 0, s[66:67]
	global_load_dwordx4 v[70:73], v[82:83], off
	v_lshl_add_u64 v[152:153], v[108:109], 0, s[66:67]
	global_load_dwordx4 v[82:85], v[152:153], off
	v_readfirstlane_b32 s79, v150
	s_and_b64 vcc, exec, s[12:13]
	s_cbranch_vccnz .LBB0_808
	s_and_b64 vcc, exec, s[98:99]
	s_cbranch_vccnz .LBB0_808
	s_add_i32 s28, s75, 0xffffff80
	s_cmp_gt_i32 s28, s73
	s_cbranch_scc1 .LBB0_808
	s_cmp_le_i32 s48, s72
	v_add_u32_e32 v150, s78, v144
	s_mov_b64 s[66:67], -1
	v_add_u32_e32 v152, s78, v145
	v_lshl_add_u32 v153, v142, 2, s71
	s_cbranch_scc0 .LBB0_805
	s_waitcnt lgkmcnt(6)
	v_pk_add_f32 v[48:49], v[126:127], v[48:49]
	v_pk_add_f32 v[44:45], v[122:123], v[44:45]
	v_pk_add_f32 v[40:41], v[118:119], v[40:41]
	v_pk_add_f32 v[36:37], v[114:115], v[36:37]
	v_pk_add_f32 v[46:47], v[124:125], v[46:47]
	v_pk_add_f32 v[42:43], v[120:121], v[42:43]
	v_pk_add_f32 v[38:39], v[116:117], v[38:39]
	v_pk_add_f32 v[34:35], v[112:113], v[34:35]
	s_waitcnt lgkmcnt(8)
	v_pk_add_f32 v[64:65], v[126:127], v[64:65]
	v_pk_add_f32 v[60:61], v[122:123], v[60:61]
	s_waitcnt lgkmcnt(7)
	v_mfma_f32_32x32x16_bf16 v[34:49], v[154:157], v[94:97], v[34:49]
	v_add_f32_e64 v56, v118, v56
	v_add_f32_e64 v57, v119, v57
	v_add_f32_e64 v52, v114, v52
	v_add_f32_e64 v53, v115, v53
	v_add_f32_e64 v62, v124, v62
	v_add_f32_e64 v63, v125, v63
	v_pk_add_f32 v[58:59], v[120:121], v[58:59]
	v_pk_add_f32 v[54:55], v[116:117], v[54:55]
	v_pk_add_f32 v[50:51], v[112:113], v[50:51]
	s_waitcnt lgkmcnt(6)
	s_nop 0
	v_mfma_f32_32x32x16_bf16 v[50:65], v[158:161], v[94:97], v[50:65]
	s_waitcnt lgkmcnt(5)
	v_mfma_f32_32x32x16_bf16 v[34:49], v[210:213], v[98:101], v[34:49]
	s_waitcnt lgkmcnt(4)
	v_mfma_f32_32x32x16_bf16 v[50:65], v[214:217], v[98:101], v[50:65]
	s_waitcnt lgkmcnt(3)
	v_mfma_f32_32x32x16_bf16 v[34:49], v[218:221], v[102:105], v[34:49]
	s_waitcnt lgkmcnt(2)
	v_mfma_f32_32x32x16_bf16 v[50:65], v[222:225], v[102:105], v[50:65]
	s_waitcnt lgkmcnt(1)
	v_mfma_f32_32x32x16_bf16 v[34:49], v[226:229], v[90:93], v[34:49]
	s_waitcnt lgkmcnt(0)
; #define LAS __attribute__((address_space(3)))
; __device__ __forceinline__ unsigned cvtpk(float lo, float hi) { typedef __bf16 bf16x2_t __attribute__((ext_vector_type(2))); f32x2 v = {lo, hi}; bf16x2_t b = __builtin_convertvector(v, bf16x2_t); return __builtin_bit_cast(unsigned, b); }
; template <bool BAND>
; __device__ __forceinline__ void tile_body(f32x16* o, float& l_reg, const bf16x8* qr, const LAS unsigned char* kbs, const LAS float* wb, int vb, float ci, int hi, int keybase, int qabs) {
;     ...
;     for (int d0 = 0; d0 < 4; ++d0) {
;         const bf16x8 b0 = *(const LAS bf16x8*)(kbs + d0 * 2048), b1 = *(const LAS bf16x8*)(kbs + d0 * 2048 + 512);
;         p0 = __builtin_amdgcn_mfma_f32_32x32x16_bf16(b0, qr[d0], p0, 0, 0, 0); p1 = __builtin_amdgcn_mfma_f32_32x32x16_bf16(b1, qr[d0], p1, 0, 0, 0); }
;     if (BAND) {
; #pragma unroll
;         for (int r = 0; r < 16; ++r) { const int key = keybase + 8 * (r >> 2) + (r & 3); if (key > qabs) p0[r] = -INFINITY; if (key + 32 > qabs) p1[r] = -INFINITY; }
;     }
;     f32x2 s2 = {0.f, 0.f};
; #pragma unroll
;     for (int r = 0; r < 16; r += 2) {
;         p0[r] = __builtin_amdgcn_exp2f(p0[r]); p0[r + 1] = __builtin_amdgcn_exp2f(p0[r + 1]); p1[r] = __builtin_amdgcn_exp2f(p1[r]); p1[r + 1] = __builtin_amdgcn_exp2f(p1[r + 1]);
;         s2 += (f32x2){p0[r], p0[r + 1]}; s2 += (f32x2){p1[r], p1[r + 1]}; }
;     l_reg += s2.x + s2.y;
;     u32x4 pw0, pw1, pw2, pw3;
;     pw0 = (u32x4){cvtpk(p0[0], p0[1]), cvtpk(p0[2], p0[3]), cvtpk(p0[4], p0[5]), cvtpk(p0[6], p0[7])};
;     pw1 = (u32x4){cvtpk(p0[8], p0[9]), cvtpk(p0[10], p0[11]), cvtpk(p0[12], p0[13]), cvtpk(p0[14], p0[15])};
;     pw2 = (u32x4){cvtpk(p1[0], p1[1]), cvtpk(p1[2], p1[3]), cvtpk(p1[4], p1[5]), cvtpk(p1[6], p1[7])};
;     pw3 = (u32x4){cvtpk(p1[8], p1[9]), cvtpk(p1[10], p1[11]), cvtpk(p1[12], p1[13]), cvtpk(p1[14], p1[15])};
;     pv(o, vb, __builtin_bit_cast(bf16x8, pw0), __builtin_bit_cast(bf16x8, pw1), __builtin_bit_cast(bf16x8, pw2), __builtin_bit_cast(bf16x8, pw3));
	v_mfma_f32_32x32x16_bf16 v[50:65], v[230:233], v[90:93], v[50:65]
	s_nop 9
	v_exp_f32_e32 v34, v34
	v_exp_f32_e32 v35, v35
	v_exp_f32_e32 v36, v36
	v_exp_f32_e32 v37, v37
	v_exp_f32_e32 v38, v38
	v_pk_add_f32 v[154:155], v[34:35], 0 op_sel_hi:[1,0]
	v_exp_f32_e32 v39, v39
	v_exp_f32_e32 v50, v50
	v_exp_f32_e32 v51, v51
	v_exp_f32_e32 v52, v52
	v_exp_f32_e32 v53, v53
	v_exp_f32_e32 v54, v54
	v_pk_add_f32 v[154:155], v[50:51], v[154:155]
	v_exp_f32_e32 v55, v55
	v_pk_add_f32 v[154:155], v[36:37], v[154:155]
	v_exp_f32_e32 v40, v40
	v_exp_f32_e32 v41, v41
	v_pk_add_f32 v[154:155], v[52:53], v[154:155]
	v_exp_f32_e32 v56, v56
	v_exp_f32_e32 v57, v57
	v_pk_add_f32 v[154:155], v[38:39], v[154:155]
	v_exp_f32_e32 v42, v42
	v_exp_f32_e32 v43, v43
	v_pk_add_f32 v[154:155], v[54:55], v[154:155]
	v_exp_f32_e32 v58, v58
	v_exp_f32_e32 v59, v59
	v_pk_add_f32 v[154:155], v[40:41], v[154:155]
	v_exp_f32_e32 v44, v44
	v_exp_f32_e32 v45, v45
	v_pk_add_f32 v[154:155], v[56:57], v[154:155]
	v_exp_f32_e32 v60, v60
	v_exp_f32_e32 v61, v61
	v_pk_add_f32 v[154:155], v[42:43], v[154:155]
	v_exp_f32_e32 v46, v46
	v_exp_f32_e32 v47, v47
	v_cvt_pk_bf16_f32 v164, v50, v51
	ds_read_b64_tr_b16 v[50:51],v150 offset:0
	v_pk_add_f32 v[154:155], v[58:59], v[154:155]
	v_exp_f32_e32 v62, v62
	v_exp_f32_e32 v63, v63
	v_cvt_pk_bf16_f32 v165, v52, v53
	ds_read_b64_tr_b16 v[52:53],v150 offset:512
	v_pk_add_f32 v[154:155], v[44:45], v[154:155]
	v_exp_f32_e32 v48, v48
	v_exp_f32_e32 v49, v49
	v_cvt_pk_bf16_f32 v166, v54, v55
	ds_read_b64_tr_b16 v[54:55],v150 offset:1024
	v_pk_add_f32 v[154:155], v[60:61], v[154:155]
	v_exp_f32_e32 v64, v64
	v_exp_f32_e32 v65, v65
	v_cvt_pk_bf16_f32 v167, v56, v57
	ds_read_b64_tr_b16 v[56:57],v150 offset:1536
	v_pk_add_f32 v[154:155], v[46:47], v[154:155]
	v_cvt_pk_bf16_f32 v168, v58, v59
	ds_read_b64_tr_b16 v[58:59],v150 offset:2048
	v_pk_add_f32 v[154:155], v[62:63], v[154:155]
	v_cvt_pk_bf16_f32 v169, v60, v61
	ds_read_b64_tr_b16 v[60:61],v150 offset:2560
	v_pk_add_f32 v[154:155], v[48:49], v[154:155]
	v_cvt_pk_bf16_f32 v170, v62, v63
	ds_read_b64_tr_b16 v[62:63],v150 offset:3072
	v_pk_add_f32 v[154:155], v[64:65], v[154:155]
	v_cvt_pk_bf16_f32 v171, v64, v65
	ds_read_b64_tr_b16 v[64:65],v150 offset:3584
	s_waitcnt lgkmcnt(0)
	v_add_f32_e32 v154, v154, v155
	v_add_f32_e32 v154, v148, v154
	v_cvt_pk_bf16_f32 v156, v34, v35
	v_cvt_pk_bf16_f32 v157, v36, v37
	v_cvt_pk_bf16_f32 v158, v38, v39
	v_cvt_pk_bf16_f32 v159, v40, v41
	v_cvt_pk_bf16_f32 v160, v42, v43
	v_cvt_pk_bf16_f32 v161, v44, v45
	v_cvt_pk_bf16_f32 v162, v46, v47
	v_cvt_pk_bf16_f32 v163, v48, v49
	v_mfma_f32_32x32x16_bf16 v[2:17], v[156:159], v[50:53], v[2:17]
	ds_read_b64_tr_b16 v[172:173],v150 offset:4096
	ds_read_b64_tr_b16 v[174:175],v150 offset:4608
	ds_read_b64_tr_b16 v[176:177],v150 offset:5120
	ds_read_b64_tr_b16 v[178:179],v150 offset:5632
	ds_read_b64_tr_b16 v[180:181],v150 offset:6144
	ds_read_b64_tr_b16 v[182:183],v150 offset:6656
	ds_read_b64_tr_b16 v[184:185],v150 offset:7168
	s_nop 0
	v_mfma_f32_32x32x16_bf16 v[2:17], v[160:163], v[54:57], v[2:17]
	ds_read_b64_tr_b16 v[186:187],v150 offset:7680
	s_waitcnt lgkmcnt(0)
	v_mfma_f32_32x32x16_bf16 v[2:17], v[164:167], v[58:61], v[2:17]
	v_mfma_f32_32x32x16_bf16 v[2:17], v[168:171], v[62:65], v[2:17]
	v_mfma_f32_32x32x16_bf16 v[18:33], v[156:159], v[172:175], v[18:33]
	s_mov_b64 s[66:67], 0
	v_mfma_f32_32x32x16_bf16 v[18:33], v[160:163], v[176:179], v[18:33]
	v_mfma_f32_32x32x16_bf16 v[18:33], v[164:167], v[180:183], v[18:33]
	v_mfma_f32_32x32x16_bf16 v[18:33], v[168:171], v[184:187], v[18:33]
.LBB0_805:
	s_andn2_b64 vcc, exec, s[66:67]
	s_cbranch_vccnz .Lmy_attjoin_B
	s_nop 4
	s_nop 0
	s_waitcnt lgkmcnt(4)
	v_pk_add_f32 v[56:57], v[118:119], v[56:57]
	s_waitcnt lgkmcnt(9)
	v_pk_add_f32 v[60:61], v[122:123], v[60:61]
	s_waitcnt lgkmcnt(8)
	v_pk_add_f32 v[64:65], v[126:127], v[64:65]
	v_pk_add_f32 v[52:53], v[114:115], v[52:53]
	v_pk_add_f32 v[62:63], v[124:125], v[62:63]
	v_pk_add_f32 v[58:59], v[120:121], v[58:59]
	v_pk_add_f32 v[54:55], v[116:117], v[54:55]
	v_pk_add_f32 v[50:51], v[112:113], v[50:51]
	v_pk_add_f32 v[48:49], v[126:127], v[48:49]
	v_pk_add_f32 v[44:45], v[122:123], v[44:45]
	v_pk_add_f32 v[40:41], v[118:119], v[40:41]
	v_pk_add_f32 v[36:37], v[114:115], v[36:37]
	v_pk_add_f32 v[46:47], v[124:125], v[46:47]
	v_pk_add_f32 v[42:43], v[120:121], v[42:43]
	v_pk_add_f32 v[38:39], v[116:117], v[38:39]
	v_pk_add_f32 v[34:35], v[112:113], v[34:35]
	s_waitcnt lgkmcnt(6)
	v_mfma_f32_32x32x16_bf16 v[50:65], v[158:161], v[94:97], v[50:65]
	v_mfma_f32_32x32x16_bf16 v[34:49], v[154:157], v[94:97], v[34:49]
	s_waitcnt lgkmcnt(4)
	v_mfma_f32_32x32x16_bf16 v[50:65], v[214:217], v[98:101], v[50:65]
	v_mfma_f32_32x32x16_bf16 v[34:49], v[210:213], v[98:101], v[34:49]
	s_waitcnt lgkmcnt(2)
	v_mfma_f32_32x32x16_bf16 v[50:65], v[222:225], v[102:105], v[50:65]
	v_mfma_f32_32x32x16_bf16 v[34:49], v[218:221], v[102:105], v[34:49]
	v_add_u32_e32 v152, s75, v142
	v_add_u32_e32 v153, 0xffffff80, v152
	s_waitcnt lgkmcnt(1)
	v_mfma_f32_32x32x16_bf16 v[50:65], v[230:233], v[90:93], v[50:65]
	v_add_u32_e32 v154, 0xffffffa0, v152
	v_cmp_le_i32_e32 vcc, v154, v147
	s_waitcnt lgkmcnt(0)
; __device__ __forceinline__ void pv(f32x16* o, int vb, bf16x8 pa0, bf16x8 pa1, bf16x8 pa2, bf16x8 pa3) {
; #pragma unroll
;     for (int d0 = 0; d0 < 2; ++d0) { s16x4 lo[4], hi[4];
; #pragma unroll
;         for (int ks = 0; ks < 4; ++ks) {
;             asm volatile("ds_read_b64_tr_b16 %0,%1 offset:%c2" : "=&v"(lo[ks]) : "v"(vb), "i"(d0 * 4096 + ks * 1024) : "memory");
;             asm volatile("ds_read_b64_tr_b16 %0,%1 offset:%c2" : "=&v"(hi[ks]) : "v"(vb), "i"(d0 * 4096 + ks * 1024 + 512) : "memory"); }
;         asm volatile("s_waitcnt lgkmcnt(0)" ::: "memory"); __builtin_amdgcn_sched_barrier(0);
;     ...
;         o[d0] = __builtin_amdgcn_mfma_f32_32x32x16_bf16(pa0, PK(0), o[d0], 0, 0, 0);
;         o[d0] = __builtin_amdgcn_mfma_f32_32x32x16_bf16(pa1, PK(1), o[d0], 0, 0, 0);
;         o[d0] = __builtin_amdgcn_mfma_f32_32x32x16_bf16(pa2, PK(2), o[d0], 0, 0, 0);
;         o[d0] = __builtin_amdgcn_mfma_f32_32x32x16_bf16(pa3, PK(3), o[d0], 0, 0, 0);
;     ...
;     }
; template <bool BAND>
; __device__ __forceinline__ void tile_body(f32x16* o, float& l_reg, const bf16x8* qr, const LAS unsigned char* kbs, const LAS float* wb, int vb, float ci, int hi, int keybase, int qabs) {
;     ...
;     if (BAND) {
; #pragma unroll
;         for (int r = 0; r < 16; ++r) { const int key = keybase + 8 * (r >> 2) + (r & 3); if (key > qabs) p0[r] = -INFINITY; if (key + 32 > qabs) p1[r] = -INFINITY; }
;     }
;     f32x2 s2 = {0.f, 0.f};
; #pragma unroll
;     for (int r = 0; r < 16; r += 2) {
;         p0[r] = __builtin_amdgcn_exp2f(p0[r]); p0[r + 1] = __builtin_amdgcn_exp2f(p0[r + 1]); p1[r] = __builtin_amdgcn_exp2f(p1[r]); p1[r + 1] = __builtin_amdgcn_exp2f(p1[r + 1]);
;         s2 += (f32x2){p0[r], p0[r + 1]}; s2 += (f32x2){p1[r], p1[r + 1]}; }
;     l_reg += s2.x + s2.y;
;     u32x4 pw0, pw1, pw2, pw3;
;     pw0 = (u32x4){cvtpk(p0[0], p0[1]), cvtpk(p0[2], p0[3]), cvtpk(p0[4], p0[5]), cvtpk(p0[6], p0[7])};
;     pw1 = (u32x4){cvtpk(p0[8], p0[9]), cvtpk(p0[10], p0[11]), cvtpk(p0[12], p0[13]), cvtpk(p0[14], p0[15])};
;     pw2 = (u32x4){cvtpk(p1[0], p1[1]), cvtpk(p1[2], p1[3]), cvtpk(p1[4], p1[5]), cvtpk(p1[6], p1[7])};
;     pw3 = (u32x4){cvtpk(p1[8], p1[9]), cvtpk(p1[10], p1[11]), cvtpk(p1[12], p1[13]), cvtpk(p1[14], p1[15])};
;     pv(o, vb, __builtin_bit_cast(bf16x8, pw0), __builtin_bit_cast(bf16x8, pw1), __builtin_bit_cast(bf16x8, pw2), __builtin_bit_cast(bf16x8, pw3));
	v_mfma_f32_32x32x16_bf16 v[34:49], v[226:229], v[90:93], v[34:49]
	s_nop 7
	v_cndmask_b32_e32 v50, v134, v50, vcc
	v_cmp_lt_i32_e32 vcc, v153, v147
	s_nop 1
	v_cndmask_b32_e32 v35, v134, v35, vcc
	v_cmp_le_i32_e32 vcc, v153, v147
	v_add_u32_e32 v153, 0xffffffa1, v152
	v_exp_f32_e32 v35, v35
	v_cndmask_b32_e32 v34, v134, v34, vcc
	v_cmp_le_i32_e32 vcc, v153, v147
	v_add_u32_e32 v153, 0xffffff82, v152
	v_exp_f32_e32 v34, v34
	v_cndmask_b32_e32 v51, v134, v51, vcc
	v_cmp_le_i32_e32 vcc, v153, v147
	v_add_u32_e32 v153, 0xffffffa2, v152
	s_nop 0
	v_cndmask_b32_e32 v36, v134, v36, vcc
	v_cmp_le_i32_e32 vcc, v153, v147
	v_add_u32_e32 v153, 0xffffff83, v152
	v_exp_f32_e32 v36, v36
	v_cndmask_b32_e32 v52, v134, v52, vcc
	v_cmp_le_i32_e32 vcc, v153, v147
	v_add_u32_e32 v153, 0xffffffa3, v152
	s_nop 0
	v_cndmask_b32_e32 v37, v134, v37, vcc
	v_cmp_le_i32_e32 vcc, v153, v147
	v_add_u32_e32 v153, 0xffffff88, v152
	v_exp_f32_e32 v37, v37
	v_cndmask_b32_e32 v53, v134, v53, vcc
	v_cmp_le_i32_e32 vcc, v153, v147
	s_nop 1
	v_cndmask_b32_e32 v153, v134, v38, vcc
	v_add_u32_e32 v38, 0xffffffa8, v152
	v_cmp_le_i32_e32 vcc, v38, v147
	v_add_u32_e32 v38, 0xffffff89, v152
	s_nop 0
	v_cndmask_b32_e32 v54, v134, v54, vcc
	v_cmp_le_i32_e32 vcc, v38, v147
	v_add_u32_e32 v38, 0xffffffa9, v152
	s_nop 0
	v_cndmask_b32_e32 v154, v134, v39, vcc
	v_cmp_le_i32_e32 vcc, v38, v147
	v_add_u32_e32 v38, 0xffffff8a, v152
	s_nop 0
	v_cndmask_b32_e32 v55, v134, v55, vcc
	v_cmp_le_i32_e32 vcc, v38, v147
	v_add_u32_e32 v38, 0xffffffaa, v152
	s_nop 0
	v_cndmask_b32_e32 v155, v134, v40, vcc
	v_cmp_le_i32_e32 vcc, v38, v147
	v_add_u32_e32 v38, 0xffffff8b, v152
	v_exp_f32_e32 v40, v153
	v_cndmask_b32_e32 v56, v134, v56, vcc
	v_cmp_le_i32_e32 vcc, v38, v147
	v_add_u32_e32 v38, 0xffffffab, v152
	s_nop 0
	v_cndmask_b32_e32 v156, v134, v41, vcc
	v_cmp_le_i32_e32 vcc, v38, v147
	v_add_u32_e32 v38, 0xffffff90, v152
	v_exp_f32_e32 v41, v154
	v_cndmask_b32_e32 v57, v134, v57, vcc
	v_cmp_le_i32_e32 vcc, v38, v147
	v_add_u32_e32 v38, 0xffffffb0, v152
	s_nop 0
	v_cndmask_b32_e32 v157, v134, v42, vcc
	v_cmp_le_i32_e32 vcc, v38, v147
	v_add_u32_e32 v38, 0xffffff91, v152
	v_exp_f32_e32 v42, v50
	v_cndmask_b32_e32 v58, v134, v58, vcc
	v_cmp_le_i32_e32 vcc, v38, v147
	v_add_u32_e32 v38, 0xffffffb1, v152
	v_exp_f32_e32 v50, v56
	v_cndmask_b32_e32 v158, v134, v43, vcc
	v_cmp_le_i32_e32 vcc, v38, v147
	v_add_u32_e32 v38, 0xffffff92, v152
	v_exp_f32_e32 v43, v51
	v_cndmask_b32_e32 v59, v134, v59, vcc
	v_cmp_le_i32_e32 vcc, v38, v147
	v_add_u32_e32 v38, 0xffffffb2, v152
	v_exp_f32_e32 v51, v57
	v_cndmask_b32_e32 v159, v134, v44, vcc
	v_cmp_le_i32_e32 vcc, v38, v147
	v_add_u32_e32 v38, 0xffffff93, v152
	v_exp_f32_e32 v44, v52
	v_cndmask_b32_e32 v60, v134, v60, vcc
	v_cmp_le_i32_e32 vcc, v38, v147
	v_add_u32_e32 v38, 0xffffffb3, v152
	v_exp_f32_e32 v52, v157
	v_cndmask_b32_e32 v160, v134, v45, vcc
	v_cmp_le_i32_e32 vcc, v38, v147
	v_add_u32_e32 v38, 0xffffff98, v152
	v_exp_f32_e32 v45, v53
	v_cndmask_b32_e32 v61, v134, v61, vcc
	v_cmp_le_i32_e32 vcc, v38, v147
	v_add_u32_e32 v38, 0xffffffb8, v152
	v_exp_f32_e32 v53, v158
	v_cndmask_b32_e32 v161, v134, v46, vcc
	v_cmp_le_i32_e32 vcc, v38, v147
	v_add_u32_e32 v38, 0xffffff99, v152
	v_exp_f32_e32 v46, v54
	v_cndmask_b32_e32 v62, v134, v62, vcc
	v_cmp_le_i32_e32 vcc, v38, v147
	v_add_u32_e32 v38, 0xffffffb9, v152
	v_exp_f32_e32 v54, v58
	v_cndmask_b32_e32 v162, v134, v47, vcc
	v_cmp_le_i32_e32 vcc, v38, v147
	v_add_u32_e32 v38, 0xffffff9a, v152
	v_exp_f32_e32 v47, v55
	v_cndmask_b32_e32 v63, v134, v63, vcc
	v_cmp_le_i32_e32 vcc, v38, v147
	v_add_u32_e32 v38, 0xffffffba, v152
	v_exp_f32_e32 v55, v59
	v_cndmask_b32_e32 v163, v134, v48, vcc
	v_cmp_le_i32_e32 vcc, v38, v147
	v_add_u32_e32 v38, 0xffffff9b, v152
	v_exp_f32_e32 v48, v155
	v_cndmask_b32_e32 v164, v134, v64, vcc
	v_cmp_le_i32_e32 vcc, v38, v147
	v_add_u32_e32 v38, 0xffffffbb, v152
	v_exp_f32_e32 v56, v159
	v_cndmask_b32_e32 v165, v134, v49, vcc
	v_cmp_le_i32_e32 vcc, v38, v147
	v_pk_add_f32 v[38:39], v[34:35], 0 op_sel_hi:[1,0]
	v_exp_f32_e32 v49, v156
	v_pk_add_f32 v[38:39], v[42:43], v[38:39]
	v_exp_f32_e32 v57, v160
	v_pk_add_f32 v[38:39], v[36:37], v[38:39]
	v_exp_f32_e32 v58, v60
	v_pk_add_f32 v[38:39], v[44:45], v[38:39]
	v_exp_f32_e32 v59, v61
	v_pk_add_f32 v[38:39], v[40:41], v[38:39]
	v_exp_f32_e32 v60, v161
	v_pk_add_f32 v[38:39], v[46:47], v[38:39]
	v_exp_f32_e32 v61, v162
	v_pk_add_f32 v[38:39], v[48:49], v[38:39]
	v_exp_f32_e32 v62, v62
	v_pk_add_f32 v[38:39], v[50:51], v[38:39]
	v_exp_f32_e32 v63, v63
	v_pk_add_f32 v[38:39], v[52:53], v[38:39]
	v_cndmask_b32_e32 v166, v134, v65, vcc
	v_pk_add_f32 v[38:39], v[54:55], v[38:39]
	v_exp_f32_e32 v64, v163
	v_pk_add_f32 v[38:39], v[56:57], v[38:39]
	v_exp_f32_e32 v65, v165
	v_pk_add_f32 v[38:39], v[58:59], v[38:39]
	v_exp_f32_e32 v152, v164
	v_exp_f32_e32 v153, v166
	v_pk_add_f32 v[38:39], v[60:61], v[38:39]
	v_cvt_pk_bf16_f32 v42, v42, v43
	v_pk_add_f32 v[38:39], v[62:63], v[38:39]
	v_cvt_pk_bf16_f32 v43, v44, v45
	v_pk_add_f32 v[38:39], v[64:65], v[38:39]
	v_cvt_pk_bf16_f32 v45, v50, v51
	v_pk_add_f32 v[38:39], v[152:153], v[38:39]
	ds_read_b64_tr_b16 v[50:51],v150 offset:0
	v_cvt_pk_bf16_f32 v44, v46, v47
	v_add_f32_e32 v38, v38, v39
	v_add_f32_e32 v154, v148, v38
	v_cvt_pk_bf16_f32 v38, v52, v53
	ds_read_b64_tr_b16 v[52:53],v150 offset:512
	v_cvt_pk_bf16_f32 v46, v54, v55
	ds_read_b64_tr_b16 v[54:55],v150 offset:1024
	v_cvt_pk_bf16_f32 v39, v56, v57
	ds_read_b64_tr_b16 v[56:57],v150 offset:1536
	v_cvt_pk_bf16_f32 v47, v58, v59
	ds_read_b64_tr_b16 v[58:59],v150 offset:2048
	v_cvt_pk_bf16_f32 v34, v34, v35
	v_cvt_pk_bf16_f32 v35, v36, v37
	v_cvt_pk_bf16_f32 v36, v40, v41
	v_cvt_pk_bf16_f32 v40, v60, v61
	ds_read_b64_tr_b16 v[60:61],v150 offset:2560
	v_cvt_pk_bf16_f32 v37, v48, v49
	v_cvt_pk_bf16_f32 v48, v62, v63
	ds_read_b64_tr_b16 v[62:63],v150 offset:3072
	v_cvt_pk_bf16_f32 v41, v64, v65
	ds_read_b64_tr_b16 v[64:65],v150 offset:3584
	s_waitcnt lgkmcnt(0)
	v_cvt_pk_bf16_f32 v49, v152, v153
	v_mfma_f32_32x32x16_bf16 v[2:17], v[34:37], v[50:53], v[2:17]
	ds_read_b64_tr_b16 v[50:51],v150 offset:4096
	ds_read_b64_tr_b16 v[52:53],v150 offset:4608
	v_mfma_f32_32x32x16_bf16 v[2:17], v[38:41], v[54:57], v[2:17]
	ds_read_b64_tr_b16 v[54:55],v150 offset:5120
	ds_read_b64_tr_b16 v[56:57],v150 offset:5632
	v_mfma_f32_32x32x16_bf16 v[2:17], v[42:45], v[58:61], v[2:17]
	ds_read_b64_tr_b16 v[58:59],v150 offset:6144
	ds_read_b64_tr_b16 v[60:61],v150 offset:6656
	ds_read_b64_tr_b16 v[156:157],v150 offset:7168
	ds_read_b64_tr_b16 v[158:159],v150 offset:7680
	s_waitcnt lgkmcnt(0)
	v_mfma_f32_32x32x16_bf16 v[2:17], v[46:49], v[62:65], v[2:17]
	v_mfma_f32_32x32x16_bf16 v[18:33], v[34:37], v[50:53], v[18:33]
	v_mfma_f32_32x32x16_bf16 v[18:33], v[38:41], v[54:57], v[18:33]
	v_mfma_f32_32x32x16_bf16 v[18:33], v[42:45], v[58:61], v[18:33]
	v_mfma_f32_32x32x16_bf16 v[18:33], v[46:49], v[156:159], v[18:33]

.LBB0_808:
	s_cmp_lg_u32 s48, 1
	v_fma_f32 v150, v151, s50, -v146
	s_cselect_b64 s[66:67], -1, 0
	v_cmp_nlt_f32_e64 s[68:69], v150, -v131
	v_fma_f32 v196, v151, s50, -v197
	v_cmp_lt_f32_e64 s[100:101], v196, -v131
	s_nop 3
	s_or_b64 s[98:99], s[98:99], s[100:101]
	s_and_b64 s[70:71], s[66:67], s[68:69]
	s_mov_b64 s[68:69], -1
	s_and_saveexec_b64 s[66:67], s[70:71]
	s_cbranch_execz .LBB0_775
	s_waitcnt lgkmcnt(0)
	s_barrier
	v_add_u32_e32 v242, s77, v145
	v_lshl_add_u32 v243, v142, 2, s76
	ds_read_b128 v[34:37], v243 offset:32768
	ds_read_b128 v[38:41], v243 offset:32800
	ds_read_b128 v[42:45], v243 offset:32832
	ds_read_b128 v[46:49], v243 offset:32864
	ds_read_b128 v[50:53], v243 offset:32896
	ds_read_b128 v[54:57], v243 offset:32928
	ds_read_b128 v[58:61], v243 offset:32960
	ds_read_b128 v[62:65], v243 offset:32992
	ds_read_b128 v[234:237], v242
	ds_read_b128 v[238:241], v242 offset:512
	ds_read_b128 v[210:213], v242 offset:2048
	ds_read_b128 v[214:217], v242 offset:2560
	ds_read_b128 v[218:221], v242 offset:4096
	ds_read_b128 v[222:225], v242 offset:4608
	ds_read_b128 v[226:229], v242 offset:6144
	ds_read_b128 v[230:233], v242 offset:6656
	s_waitcnt vmcnt(6)
	s_nop 1
	v_add_f32_dpp v150, v139, v139 row_shl:1 row_mask:0xf bank_mask:0xf bound_ctrl:1
	s_nop 1
	v_add_f32_dpp v150, v150, v150 row_shl:2 row_mask:0xf bank_mask:0xf bound_ctrl:1
	s_nop 1
	v_add_f32_dpp v150, v150, v150 row_shl:4 row_mask:0xf bank_mask:0xf bound_ctrl:1
	s_nop 1
	v_add_f32_dpp v150, v150, v150 row_shl:8 row_mask:0xf bank_mask:0xf bound_ctrl:1
	s_nop 0
	v_readlane_b32 s28, v150, 16
	v_readlane_b32 s80, v150, 32
	v_readlane_b32 s78, v150, 48
	s_and_saveexec_b64 s[68:69], s[6:7]
	s_xor_b64 s[68:69], exec, s[68:69]
	s_cbranch_execz .LBB0_815
	s_and_saveexec_b64 s[70:71], s[8:9]
	s_xor_b64 s[70:71], exec, s[70:71]
	v_mov_b32_e32 v152, s78
	v_cndmask_b32_e64 v152, 0, v152, s[10:11]
	s_andn2_saveexec_b64 s[70:71], s[70:71]
	v_mov_b32_e32 v152, s78
	v_add_f32_e32 v152, s80, v152
	s_or_b64 exec, exec, s[70:71]

; #define LAS __attribute__((address_space(3)))
; template <bool BAND>
; __device__ __forceinline__ void tile_body(f32x16* o, float& l_reg, const bf16x8* qr, const LAS unsigned char* kbs, const LAS float* wb, int vb, float ci, int hi, int keybase, int qabs) {
;     ...
; #pragma unroll
;     for (int g4 = 0; g4 < 4; ++g4) {
;         const f32x4 ba = *(const LAS f32x4*)(wb + 8 * g4 + 4 * hi) + ci, bb = *(const LAS f32x4*)(wb + 32 + 8 * g4 + 4 * hi) + ci;
; #pragma unroll
;         for (int e = 0; e < 4; ++e) { p0[4 * g4 + e] = ba[e]; p1[4 * g4 + e] = bb[e]; }
;     }
; #pragma unroll
;     for (int d0 = 0; d0 < 4; ++d0) {
;         const bf16x8 b0 = *(const LAS bf16x8*)(kbs + d0 * 2048), b1 = *(const LAS bf16x8*)(kbs + d0 * 2048 + 512);
;         p0 = __builtin_amdgcn_mfma_f32_32x32x16_bf16(b0, qr[d0], p0, 0, 0, 0); p1 = __builtin_amdgcn_mfma_f32_32x32x16_bf16(b1, qr[d0], p1, 0, 0, 0); }
;     if (BAND) {
; #pragma unroll
;         for (int r = 0; r < 16; ++r) { const int key = keybase + 8 * (r >> 2) + (r & 3); if (key > qabs) p0[r] = -INFINITY; if (key + 32 > qabs) p1[r] = -INFINITY; }
.LBB0_819:
	s_andn2_b64 vcc, exec, s[68:69]
	s_cbranch_vccnz .LBB0_774
	s_and_b64 vcc, exec, s[98:99]
	s_cbranch_vccnz .LBB0_774
	s_add_i32 s28, s75, 0xffffff40
	s_cmp_gt_i32 s28, s73
	s_cbranch_scc1 .LBB0_774
	s_add_i32 s68, s48, -2
	s_cmp_lt_i32 s68, s72
	v_add_u32_e32 v0, s77, v144
	s_mov_b64 s[68:69], -1
	v_add_u32_e32 v149, s77, v145
	v_lshl_add_u32 v150, v142, 2, s76
	s_cbranch_scc1 .LBB0_823
	s_waitcnt lgkmcnt(4)
	v_pk_add_f32 v[56:57], v[118:119], v[56:57]
	s_waitcnt lgkmcnt(9)
	v_pk_add_f32 v[60:61], v[122:123], v[60:61]
	s_waitcnt lgkmcnt(8)
	v_pk_add_f32 v[64:65], v[126:127], v[64:65]
	v_pk_add_f32 v[52:53], v[114:115], v[52:53]
	v_pk_add_f32 v[62:63], v[124:125], v[62:63]
	v_pk_add_f32 v[58:59], v[120:121], v[58:59]
	v_pk_add_f32 v[54:55], v[116:117], v[54:55]
	v_pk_add_f32 v[50:51], v[112:113], v[50:51]
	v_pk_add_f32 v[48:49], v[126:127], v[48:49]
	v_pk_add_f32 v[44:45], v[122:123], v[44:45]
	v_pk_add_f32 v[40:41], v[118:119], v[40:41]
	v_pk_add_f32 v[36:37], v[114:115], v[36:37]
	v_pk_add_f32 v[46:47], v[124:125], v[46:47]
	v_pk_add_f32 v[42:43], v[120:121], v[42:43]
	v_pk_add_f32 v[38:39], v[116:117], v[38:39]
	v_pk_add_f32 v[34:35], v[112:113], v[34:35]
	s_waitcnt lgkmcnt(6)
	v_mfma_f32_32x32x16_bf16 v[50:65], v[238:241], v[94:97], v[50:65]
	v_mfma_f32_32x32x16_bf16 v[34:49], v[234:237], v[94:97], v[34:49]
	s_waitcnt lgkmcnt(4)
	v_mfma_f32_32x32x16_bf16 v[50:65], v[214:217], v[98:101], v[50:65]
	v_mfma_f32_32x32x16_bf16 v[34:49], v[210:213], v[98:101], v[34:49]
	s_waitcnt lgkmcnt(2)
	v_mfma_f32_32x32x16_bf16 v[50:65], v[222:225], v[102:105], v[50:65]
	v_mfma_f32_32x32x16_bf16 v[34:49], v[218:221], v[102:105], v[34:49]
	s_waitcnt lgkmcnt(1)
	v_mfma_f32_32x32x16_bf16 v[50:65], v[230:233], v[90:93], v[50:65]
	v_add_u32_e32 v152, s75, v142
	v_add_u32_e32 v154, 0xffffff60, v152
	v_add_u32_e32 v153, 0xffffff40, v152
	v_cmp_le_i32_e32 vcc, v154, v147
	s_waitcnt lgkmcnt(0)
	v_mfma_f32_32x32x16_bf16 v[34:49], v[226:229], v[90:93], v[34:49]
	s_nop 5
	v_cndmask_b32_e32 v50, v134, v50, vcc
	v_cmp_lt_i32_e32 vcc, v153, v147
	s_nop 3
	v_cndmask_b32_e32 v35, v134, v35, vcc
	v_cmp_le_i32_e32 vcc, v153, v147
	v_add_u32_e32 v153, 0xffffff61, v152
	v_exp_f32_e32 v35, v35
	v_cndmask_b32_e32 v34, v134, v34, vcc
	v_cmp_le_i32_e32 vcc, v153, v147
	v_add_u32_e32 v153, 0xffffff42, v152
	v_exp_f32_e32 v34, v34
	v_cndmask_b32_e32 v51, v134, v51, vcc
	v_cmp_le_i32_e32 vcc, v153, v147
	s_nop 1
	v_cndmask_b32_e32 v153, v134, v36, vcc
	v_add_u32_e32 v36, 0xffffff62, v152
	v_cmp_le_i32_e32 vcc, v36, v147
	v_add_u32_e32 v36, 0xffffff43, v152
	s_nop 0
	v_cndmask_b32_e32 v52, v134, v52, vcc
	v_cmp_le_i32_e32 vcc, v36, v147
	v_add_u32_e32 v36, 0xffffff63, v152
	s_nop 0
	v_cndmask_b32_e32 v154, v134, v37, vcc
	v_cmp_le_i32_e32 vcc, v36, v147
	v_add_u32_e32 v36, 0xffffff48, v152
	v_exp_f32_e32 v37, v51
	v_cndmask_b32_e32 v53, v134, v53, vcc
	v_cmp_le_i32_e32 vcc, v36, v147
	v_add_u32_e32 v36, 0xffffff68, v152
	s_nop 0
	v_cndmask_b32_e32 v155, v134, v38, vcc
	v_cmp_le_i32_e32 vcc, v36, v147
	v_add_u32_e32 v36, 0xffffff49, v152
	v_exp_f32_e32 v38, v153
	v_cndmask_b32_e32 v54, v134, v54, vcc
	v_cmp_le_i32_e32 vcc, v36, v147
	v_add_u32_e32 v36, 0xffffff69, v152
	s_nop 0
	v_cndmask_b32_e32 v156, v134, v39, vcc
	v_cmp_le_i32_e32 vcc, v36, v147
	v_add_u32_e32 v36, 0xffffff4a, v152
	v_exp_f32_e32 v39, v154
	v_cndmask_b32_e32 v55, v134, v55, vcc
	v_cmp_le_i32_e32 vcc, v36, v147
	v_add_u32_e32 v36, 0xffffff6a, v152
	v_cvt_pk_bf16_f32 v154, v34, v35
	v_cndmask_b32_e32 v157, v134, v40, vcc
	v_cmp_le_i32_e32 vcc, v36, v147
	v_add_u32_e32 v36, 0xffffff4b, v152
	v_exp_f32_e32 v40, v52
	v_cndmask_b32_e32 v56, v134, v56, vcc
	v_cmp_le_i32_e32 vcc, v36, v147
	v_add_u32_e32 v36, 0xffffff6b, v152
	s_nop 0
	v_cndmask_b32_e32 v158, v134, v41, vcc
	v_cmp_le_i32_e32 vcc, v36, v147
	v_add_u32_e32 v36, 0xffffff50, v152
	v_exp_f32_e32 v41, v53
	v_cndmask_b32_e32 v57, v134, v57, vcc
	v_cmp_le_i32_e32 vcc, v36, v147
	v_add_u32_e32 v36, 0xffffff70, v152
	v_exp_f32_e32 v51, v57
	v_cndmask_b32_e32 v159, v134, v42, vcc
	v_cmp_le_i32_e32 vcc, v36, v147
	v_add_u32_e32 v36, 0xffffff51, v152
	v_exp_f32_e32 v52, v159
	v_cndmask_b32_e32 v58, v134, v58, vcc
	v_cmp_le_i32_e32 vcc, v36, v147
	v_add_u32_e32 v36, 0xffffff71, v152
	s_nop 0
	v_cndmask_b32_e32 v160, v134, v43, vcc
	v_cmp_le_i32_e32 vcc, v36, v147
	v_add_u32_e32 v36, 0xffffff52, v152
	v_pk_add_f32 v[42:43], v[34:35], 0 op_sel_hi:[1,0]
	v_cndmask_b32_e32 v59, v134, v59, vcc
	v_cmp_le_i32_e32 vcc, v36, v147
	v_add_u32_e32 v36, 0xffffff72, v152
	v_exp_f32_e32 v53, v160
	v_cndmask_b32_e32 v161, v134, v44, vcc
	v_cmp_le_i32_e32 vcc, v36, v147
	v_add_u32_e32 v36, 0xffffff53, v152
	v_exp_f32_e32 v44, v155
	v_cndmask_b32_e32 v60, v134, v60, vcc
	v_cmp_le_i32_e32 vcc, v36, v147
	v_add_u32_e32 v36, 0xffffff73, v152
	v_cvt_pk_bf16_f32 v155, v38, v39
	v_cndmask_b32_e32 v162, v134, v45, vcc
	v_cmp_le_i32_e32 vcc, v36, v147
	v_add_u32_e32 v36, 0xffffff58, v152
	v_exp_f32_e32 v45, v156
	v_cndmask_b32_e32 v61, v134, v61, vcc
	v_cmp_le_i32_e32 vcc, v36, v147
	v_add_u32_e32 v36, 0xffffff78, v152
	v_exp_f32_e32 v57, v162
	v_cndmask_b32_e32 v163, v134, v46, vcc
	v_cmp_le_i32_e32 vcc, v36, v147
	v_add_u32_e32 v36, 0xffffff59, v152
	v_exp_f32_e32 v46, v54
	v_cndmask_b32_e32 v62, v134, v62, vcc
	v_cmp_le_i32_e32 vcc, v36, v147
	v_add_u32_e32 v36, 0xffffff79, v152
	v_exp_f32_e32 v54, v58
	v_cndmask_b32_e32 v164, v134, v47, vcc
	v_cmp_le_i32_e32 vcc, v36, v147
	v_add_u32_e32 v36, 0xffffff5a, v152
	v_exp_f32_e32 v47, v55
	v_cndmask_b32_e32 v63, v134, v63, vcc
	v_cmp_le_i32_e32 vcc, v36, v147
	v_add_u32_e32 v36, 0xffffff7a, v152
	v_exp_f32_e32 v55, v59
; __device__ __forceinline__ unsigned cvtpk(float lo, float hi) { typedef __bf16 bf16x2_t __attribute__((ext_vector_type(2))); f32x2 v = {lo, hi}; bf16x2_t b = __builtin_convertvector(v, bf16x2_t); return __builtin_bit_cast(unsigned, b); }
; template <bool BAND>
; __device__ __forceinline__ void tile_body(f32x16* o, float& l_reg, const bf16x8* qr, const LAS unsigned char* kbs, const LAS float* wb, int vb, float ci, int hi, int keybase, int qabs) {
;     ...
;     if (BAND) {
; #pragma unroll
;         for (int r = 0; r < 16; ++r) { const int key = keybase + 8 * (r >> 2) + (r & 3); if (key > qabs) p0[r] = -INFINITY; if (key + 32 > qabs) p1[r] = -INFINITY; }
;     }
;     f32x2 s2 = {0.f, 0.f};
; #pragma unroll
;     for (int r = 0; r < 16; r += 2) {
;         p0[r] = __builtin_amdgcn_exp2f(p0[r]); p0[r + 1] = __builtin_amdgcn_exp2f(p0[r + 1]); p1[r] = __builtin_amdgcn_exp2f(p1[r]); p1[r + 1] = __builtin_amdgcn_exp2f(p1[r + 1]);
;         s2 += (f32x2){p0[r], p0[r + 1]}; s2 += (f32x2){p1[r], p1[r + 1]}; }
;     l_reg += s2.x + s2.y;
;     u32x4 pw0, pw1, pw2, pw3;
;     pw0 = (u32x4){cvtpk(p0[0], p0[1]), cvtpk(p0[2], p0[3]), cvtpk(p0[4], p0[5]), cvtpk(p0[6], p0[7])};
;     pw1 = (u32x4){cvtpk(p0[8], p0[9]), cvtpk(p0[10], p0[11]), cvtpk(p0[12], p0[13]), cvtpk(p0[14], p0[15])};
;     pw2 = (u32x4){cvtpk(p1[0], p1[1]), cvtpk(p1[2], p1[3]), cvtpk(p1[4], p1[5]), cvtpk(p1[6], p1[7])};
;     pw3 = (u32x4){cvtpk(p1[8], p1[9]), cvtpk(p1[10], p1[11]), cvtpk(p1[12], p1[13]), cvtpk(p1[14], p1[15])};
;     pv(o, vb, __builtin_bit_cast(bf16x8, pw0), __builtin_bit_cast(bf16x8, pw1), __builtin_bit_cast(bf16x8, pw2), __builtin_bit_cast(bf16x8, pw3));
	v_cndmask_b32_e32 v165, v134, v48, vcc
	v_cmp_le_i32_e32 vcc, v36, v147
	v_add_u32_e32 v36, 0xffffff5b, v152
	v_exp_f32_e32 v48, v157
	v_cndmask_b32_e32 v166, v134, v64, vcc
	v_cmp_le_i32_e32 vcc, v36, v147
	v_add_u32_e32 v36, 0xffffff7b, v152
	v_exp_f32_e32 v58, v60
	v_cndmask_b32_e32 v167, v134, v49, vcc
	v_cmp_le_i32_e32 vcc, v36, v147
	v_exp_f32_e32 v36, v50
	v_exp_f32_e32 v49, v158
	v_exp_f32_e32 v50, v56
	v_exp_f32_e32 v56, v161
	v_pk_add_f32 v[42:43], v[36:37], v[42:43]
	v_exp_f32_e32 v59, v61
	v_pk_add_f32 v[42:43], v[38:39], v[42:43]
	v_exp_f32_e32 v64, v165
	v_pk_add_f32 v[42:43], v[40:41], v[42:43]
	v_cvt_pk_bf16_f32 v165, v50, v51
	v_pk_add_f32 v[42:43], v[44:45], v[42:43]
	v_exp_f32_e32 v60, v163
	v_pk_add_f32 v[42:43], v[46:47], v[42:43]
	v_exp_f32_e32 v61, v164
	v_pk_add_f32 v[42:43], v[48:49], v[42:43]
	v_cvt_pk_bf16_f32 v158, v52, v53
	v_pk_add_f32 v[42:43], v[50:51], v[42:43]
	ds_read_b64_tr_b16 v[50:51],v0 offset:0
	v_exp_f32_e32 v62, v62
	v_pk_add_f32 v[42:43], v[52:53], v[42:43]
	ds_read_b64_tr_b16 v[52:53],v0 offset:512
	v_exp_f32_e32 v63, v63
	v_pk_add_f32 v[42:43], v[54:55], v[42:43]
	v_exp_f32_e32 v170, v166
	v_cvt_pk_bf16_f32 v166, v54, v55
	ds_read_b64_tr_b16 v[54:55],v0 offset:1024
	v_cndmask_b32_e32 v152, v134, v65, vcc
	v_pk_add_f32 v[42:43], v[56:57], v[42:43]
	v_exp_f32_e32 v65, v167
	v_cvt_pk_bf16_f32 v159, v56, v57
	ds_read_b64_tr_b16 v[56:57],v0 offset:1536
	v_pk_add_f32 v[42:43], v[58:59], v[42:43]
	v_exp_f32_e32 v171, v152
	v_cvt_pk_bf16_f32 v167, v58, v59
	ds_read_b64_tr_b16 v[58:59],v0 offset:2048
	v_pk_add_f32 v[42:43], v[60:61], v[42:43]
	v_cvt_pk_bf16_f32 v160, v60, v61
	ds_read_b64_tr_b16 v[60:61],v0 offset:2560
	v_pk_add_f32 v[42:43], v[62:63], v[42:43]
	v_cvt_pk_bf16_f32 v168, v62, v63
	ds_read_b64_tr_b16 v[62:63],v0 offset:3072
	v_pk_add_f32 v[42:43], v[64:65], v[42:43]
	v_cvt_pk_bf16_f32 v161, v64, v65
	ds_read_b64_tr_b16 v[64:65],v0 offset:3584
	v_pk_add_f32 v[42:43], v[170:171], v[42:43]
	s_waitcnt lgkmcnt(0)
	v_cvt_pk_bf16_f32 v156, v44, v45
	v_add_f32_e32 v42, v42, v43
	v_add_f32_e32 v152, v148, v42
	v_cvt_pk_bf16_f32 v157, v48, v49
	v_cvt_pk_bf16_f32 v162, v36, v37
	v_cvt_pk_bf16_f32 v163, v40, v41
	v_cvt_pk_bf16_f32 v164, v46, v47
	v_cvt_pk_bf16_f32 v169, v170, v171
	v_mfma_f32_32x32x16_bf16 v[2:17], v[154:157], v[50:53], v[2:17]
	ds_read_b64_tr_b16 v[170:171],v0 offset:4096
	ds_read_b64_tr_b16 v[172:173],v0 offset:4608
	ds_read_b64_tr_b16 v[174:175],v0 offset:5120
	ds_read_b64_tr_b16 v[176:177],v0 offset:5632
	ds_read_b64_tr_b16 v[178:179],v0 offset:6144
	ds_read_b64_tr_b16 v[180:181],v0 offset:6656
	ds_read_b64_tr_b16 v[182:183],v0 offset:7168
	v_mfma_f32_32x32x16_bf16 v[2:17], v[158:161], v[54:57], v[2:17]
	ds_read_b64_tr_b16 v[184:185],v0 offset:7680
	s_waitcnt lgkmcnt(0)
	v_mfma_f32_32x32x16_bf16 v[2:17], v[162:165], v[58:61], v[2:17]
	v_mfma_f32_32x32x16_bf16 v[2:17], v[166:169], v[62:65], v[2:17]
	v_mfma_f32_32x32x16_bf16 v[18:33], v[154:157], v[170:173], v[18:33]
	s_mov_b64 s[68:69], 0
	v_mfma_f32_32x32x16_bf16 v[18:33], v[158:161], v[174:177], v[18:33]
	v_mfma_f32_32x32x16_bf16 v[18:33], v[162:165], v[178:181], v[18:33]
	v_mfma_f32_32x32x16_bf16 v[18:33], v[166:169], v[182:185], v[18:33]
; #define LAS __attribute__((address_space(3)))
; __device__ __forceinline__ unsigned cvtpk(float lo, float hi) { typedef __bf16 bf16x2_t __attribute__((ext_vector_type(2))); f32x2 v = {lo, hi}; bf16x2_t b = __builtin_convertvector(v, bf16x2_t); return __builtin_bit_cast(unsigned, b); }
; template <bool BAND>
; __device__ __forceinline__ void tile_body(f32x16* o, float& l_reg, const bf16x8* qr, const LAS unsigned char* kbs, const LAS float* wb, int vb, float ci, int hi, int keybase, int qabs) {
;     ...
; #pragma unroll
;     for (int g4 = 0; g4 < 4; ++g4) {
;         const f32x4 ba = *(const LAS f32x4*)(wb + 8 * g4 + 4 * hi) + ci, bb = *(const LAS f32x4*)(wb + 32 + 8 * g4 + 4 * hi) + ci;
; #pragma unroll
;         for (int e = 0; e < 4; ++e) { p0[4 * g4 + e] = ba[e]; p1[4 * g4 + e] = bb[e]; }
;     }
; #pragma unroll
;     for (int d0 = 0; d0 < 4; ++d0) {
;         const bf16x8 b0 = *(const LAS bf16x8*)(kbs + d0 * 2048), b1 = *(const LAS bf16x8*)(kbs + d0 * 2048 + 512);
;         p0 = __builtin_amdgcn_mfma_f32_32x32x16_bf16(b0, qr[d0], p0, 0, 0, 0); p1 = __builtin_amdgcn_mfma_f32_32x32x16_bf16(b1, qr[d0], p1, 0, 0, 0); }
;     if (BAND) {
; #pragma unroll
;         for (int r = 0; r < 16; ++r) { const int key = keybase + 8 * (r >> 2) + (r & 3); if (key > qabs) p0[r] = -INFINITY; if (key + 32 > qabs) p1[r] = -INFINITY; }
;     }
;     f32x2 s2 = {0.f, 0.f};
; #pragma unroll
;     for (int r = 0; r < 16; r += 2) {
;         p0[r] = __builtin_amdgcn_exp2f(p0[r]); p0[r + 1] = __builtin_amdgcn_exp2f(p0[r + 1]); p1[r] = __builtin_amdgcn_exp2f(p1[r]); p1[r + 1] = __builtin_amdgcn_exp2f(p1[r + 1]);
;         s2 += (f32x2){p0[r], p0[r + 1]}; s2 += (f32x2){p1[r], p1[r + 1]}; }
;     l_reg += s2.x + s2.y;
;     u32x4 pw0, pw1, pw2, pw3;
;     pw0 = (u32x4){cvtpk(p0[0], p0[1]), cvtpk(p0[2], p0[3]), cvtpk(p0[4], p0[5]), cvtpk(p0[6], p0[7])};
;     pw1 = (u32x4){cvtpk(p0[8], p0[9]), cvtpk(p0[10], p0[11]), cvtpk(p0[12], p0[13]), cvtpk(p0[14], p0[15])};
;     pw2 = (u32x4){cvtpk(p1[0], p1[1]), cvtpk(p1[2], p1[3]), cvtpk(p1[4], p1[5]), cvtpk(p1[6], p1[7])};
;     pw3 = (u32x4){cvtpk(p1[8], p1[9]), cvtpk(p1[10], p1[11]), cvtpk(p1[12], p1[13]), cvtpk(p1[14], p1[15])};
;     pv(o, vb, __builtin_bit_cast(bf16x8, pw0), __builtin_bit_cast(bf16x8, pw1), __builtin_bit_cast(bf16x8, pw2), __builtin_bit_cast(bf16x8, pw3));
.LBB0_823:
	s_andn2_b64 vcc, exec, s[68:69]
	s_cbranch_vccnz .Lmy_attjoin_C
	s_nop 4
	s_nop 0
	s_waitcnt lgkmcnt(6)
	v_pk_add_f32 v[48:49], v[126:127], v[48:49]
	v_pk_add_f32 v[44:45], v[122:123], v[44:45]
	v_pk_add_f32 v[40:41], v[118:119], v[40:41]
	v_pk_add_f32 v[36:37], v[114:115], v[36:37]
	v_pk_add_f32 v[46:47], v[124:125], v[46:47]
	v_pk_add_f32 v[42:43], v[120:121], v[42:43]
	v_pk_add_f32 v[38:39], v[116:117], v[38:39]
	v_pk_add_f32 v[34:35], v[112:113], v[34:35]
	s_waitcnt lgkmcnt(8)
	v_pk_add_f32 v[64:65], v[126:127], v[64:65]
	v_pk_add_f32 v[60:61], v[122:123], v[60:61]
	s_waitcnt lgkmcnt(7)
	v_mfma_f32_32x32x16_bf16 v[34:49], v[234:237], v[94:97], v[34:49]
	v_add_f32_e64 v56, v118, v56
	v_add_f32_e64 v57, v119, v57
	v_add_f32_e64 v52, v114, v52
	v_add_f32_e64 v53, v115, v53
	v_add_f32_e64 v62, v124, v62
	v_add_f32_e64 v63, v125, v63
	v_pk_add_f32 v[58:59], v[120:121], v[58:59]
	v_pk_add_f32 v[54:55], v[116:117], v[54:55]
	v_pk_add_f32 v[50:51], v[112:113], v[50:51]
	s_waitcnt lgkmcnt(6)
	s_nop 0
	v_mfma_f32_32x32x16_bf16 v[50:65], v[238:241], v[94:97], v[50:65]
	s_waitcnt lgkmcnt(5)
	v_mfma_f32_32x32x16_bf16 v[34:49], v[210:213], v[98:101], v[34:49]
	s_waitcnt lgkmcnt(4)
	v_mfma_f32_32x32x16_bf16 v[50:65], v[214:217], v[98:101], v[50:65]
	s_waitcnt lgkmcnt(3)
	v_mfma_f32_32x32x16_bf16 v[34:49], v[218:221], v[102:105], v[34:49]
	s_waitcnt lgkmcnt(2)
	v_mfma_f32_32x32x16_bf16 v[50:65], v[222:225], v[102:105], v[50:65]
	s_waitcnt lgkmcnt(1)
	v_mfma_f32_32x32x16_bf16 v[34:49], v[226:229], v[90:93], v[34:49]
	s_waitcnt lgkmcnt(0)
	v_mfma_f32_32x32x16_bf16 v[50:65], v[230:233], v[90:93], v[50:65]
	s_nop 9
	v_exp_f32_e32 v34, v34
	v_exp_f32_e32 v35, v35
	v_exp_f32_e32 v36, v36
	v_exp_f32_e32 v37, v37
	v_exp_f32_e32 v38, v38
	v_pk_add_f32 v[152:153], v[34:35], 0 op_sel_hi:[1,0]
	v_exp_f32_e32 v39, v39
	v_exp_f32_e32 v50, v50
	v_exp_f32_e32 v51, v51
	v_exp_f32_e32 v52, v52
	v_exp_f32_e32 v53, v53
	v_exp_f32_e32 v54, v54
	v_pk_add_f32 v[152:153], v[50:51], v[152:153]
	v_exp_f32_e32 v55, v55
	v_pk_add_f32 v[152:153], v[36:37], v[152:153]
	v_exp_f32_e32 v40, v40
	v_exp_f32_e32 v41, v41
	v_pk_add_f32 v[152:153], v[52:53], v[152:153]
	v_exp_f32_e32 v56, v56
	v_exp_f32_e32 v57, v57
	v_pk_add_f32 v[152:153], v[38:39], v[152:153]
	v_exp_f32_e32 v42, v42
	v_exp_f32_e32 v43, v43
	v_pk_add_f32 v[152:153], v[54:55], v[152:153]
	v_exp_f32_e32 v58, v58
	v_exp_f32_e32 v59, v59
	v_pk_add_f32 v[152:153], v[40:41], v[152:153]
	v_exp_f32_e32 v44, v44
	v_exp_f32_e32 v45, v45
	v_pk_add_f32 v[152:153], v[56:57], v[152:153]
	v_exp_f32_e32 v60, v60
	v_exp_f32_e32 v61, v61
	v_pk_add_f32 v[152:153], v[42:43], v[152:153]
	v_exp_f32_e32 v46, v46
	v_exp_f32_e32 v47, v47
	v_cvt_pk_bf16_f32 v34, v34, v35
	v_cvt_pk_bf16_f32 v35, v36, v37
	v_cvt_pk_bf16_f32 v36, v38, v39
	v_cvt_pk_bf16_f32 v38, v42, v43
	v_cvt_pk_bf16_f32 v42, v50, v51
	ds_read_b64_tr_b16 v[50:51],v0 offset:0
	v_pk_add_f32 v[152:153], v[58:59], v[152:153]
	v_exp_f32_e32 v62, v62
	v_exp_f32_e32 v63, v63
	v_cvt_pk_bf16_f32 v43, v52, v53
	ds_read_b64_tr_b16 v[52:53],v0 offset:512
	v_pk_add_f32 v[152:153], v[44:45], v[152:153]
	v_exp_f32_e32 v48, v48
	v_exp_f32_e32 v49, v49
	v_cvt_pk_bf16_f32 v39, v44, v45
	v_cvt_pk_bf16_f32 v44, v54, v55
	ds_read_b64_tr_b16 v[54:55],v0 offset:1024
	v_pk_add_f32 v[152:153], v[60:61], v[152:153]
	v_exp_f32_e32 v64, v64
	v_exp_f32_e32 v65, v65
	v_cvt_pk_bf16_f32 v45, v56, v57
	ds_read_b64_tr_b16 v[56:57],v0 offset:1536
	v_pk_add_f32 v[152:153], v[46:47], v[152:153]
	v_cvt_pk_bf16_f32 v37, v40, v41
	v_cvt_pk_bf16_f32 v40, v46, v47
	v_cvt_pk_bf16_f32 v46, v58, v59
	ds_read_b64_tr_b16 v[58:59],v0 offset:2048
	v_pk_add_f32 v[152:153], v[62:63], v[152:153]
	v_cvt_pk_bf16_f32 v47, v60, v61
	ds_read_b64_tr_b16 v[60:61],v0 offset:2560
	v_pk_add_f32 v[152:153], v[48:49], v[152:153]
	v_cvt_pk_bf16_f32 v41, v48, v49
	v_cvt_pk_bf16_f32 v48, v62, v63
	ds_read_b64_tr_b16 v[62:63],v0 offset:3072
	v_pk_add_f32 v[152:153], v[64:65], v[152:153]
	v_cvt_pk_bf16_f32 v49, v64, v65
	ds_read_b64_tr_b16 v[64:65],v0 offset:3584
	s_waitcnt lgkmcnt(0)
	v_add_f32_e32 v149, v152, v153
	v_add_f32_e32 v152, v148, v149
	v_mfma_f32_32x32x16_bf16 v[2:17], v[34:37], v[50:53], v[2:17]
	ds_read_b64_tr_b16 v[50:51],v0 offset:4096
	ds_read_b64_tr_b16 v[52:53],v0 offset:4608
	v_mfma_f32_32x32x16_bf16 v[2:17], v[38:41], v[54:57], v[2:17]
	ds_read_b64_tr_b16 v[54:55],v0 offset:5120
	ds_read_b64_tr_b16 v[56:57],v0 offset:5632
	v_mfma_f32_32x32x16_bf16 v[2:17], v[42:45], v[58:61], v[2:17]
	ds_read_b64_tr_b16 v[58:59],v0 offset:6144
	ds_read_b64_tr_b16 v[60:61],v0 offset:6656
	ds_read_b64_tr_b16 v[154:155],v0 offset:7168
	ds_read_b64_tr_b16 v[156:157],v0 offset:7680
	s_waitcnt lgkmcnt(0)
	v_mfma_f32_32x32x16_bf16 v[2:17], v[46:49], v[62:65], v[2:17]
	v_mfma_f32_32x32x16_bf16 v[18:33], v[34:37], v[50:53], v[18:33]
	v_mfma_f32_32x32x16_bf16 v[18:33], v[38:41], v[54:57], v[18:33]
	v_mfma_f32_32x32x16_bf16 v[18:33], v[42:45], v[58:61], v[18:33]
	v_mfma_f32_32x32x16_bf16 v[18:33], v[46:49], v[154:157], v[18:33]
	s_branch .Lmy_attjoin_C
